# v24 + EpiResid: first 32-row group of y prefetched in the tile prologue, groups 2/3 issued one group ahead
# speedup vs baseline: 1.0227x; 1.0227x over previous
.LBB0_680:
	s_waitcnt vmcnt(0)
	ds_write_b32 v2, v246
	v_ashrrev_i32_e32 v103, 6, v100
	v_lshrrev_b32_e32 v0, 30, v103
	v_add_u32_e32 v0, v103, v0
	v_ashrrev_i32_e32 v10, 2, v0
	v_mul_i32_i24_e32 v0, 4, v10
	v_ashrrev_i32_e32 v6, 3, v100
	v_sub_u32_e32 v11, v103, v0
	v_lshrrev_b32_e32 v13, 4, v100
	v_add_u32_e32 v0, s4, v6
	v_xor_b32_e32 v7, v13, v100
	v_ashrrev_i32_e32 v1, 31, v0
	v_lshlrev_b64 v[0:1], 11, v[0:1]
	v_lshlrev_b32_e32 v7, 4, v7
	v_lshlrev_b32_e32 v109, 4, v100
	s_and_b32 s8, s2, 0xffffff00
	v_lshl_add_u64 v[4:5], s[50:51], 0, v[0:1]
	v_and_b32_e32 v128, 0x70, v7
	v_readfirstlane_b32 s2, v109
	v_add_u32_e32 v14, 0x2000, v109
	v_lshl_add_u64 v[4:5], v[4:5], 0, v[128:129]
	s_mov_b32 m0, s2
	s_mov_b64 s[10:11], 0x20000
	v_readfirstlane_b32 s2, v14
	ds_write_b32 v2, v3 offset:2048
	v_lshl_add_u64 v[2:3], v[4:5], 0, s[10:11]
	s_mov_b32 m0, s2
	s_mov_b64 s[12:13], 0x40000
	v_lshl_add_u64 v[2:3], v[4:5], 0, s[12:13]
	v_add_u32_e32 v4, 0x4000, v109
	v_add_u32_e32 v6, s8, v6
	v_readfirstlane_b32 s2, v4
	v_ashrrev_i32_e32 v7, 31, v6
	s_mov_b32 m0, s2
	v_lshlrev_b64 v[6:7], 11, v[6:7]
	v_add_u32_e32 v2, 0x6000, v109
	v_lshl_add_u64 v[8:9], s[60:61], 0, v[6:7]
	v_readfirstlane_b32 s2, v2
	v_add_u32_e32 v4, 0x8000, v109
	v_lshl_add_u64 v[8:9], v[8:9], 0, v[128:129]
	s_mov_b32 m0, s2
	v_readfirstlane_b32 s2, v4
	v_add_u32_e32 v4, 0xa000, v109
	v_lshl_add_u64 v[2:3], v[8:9], 0, s[10:11]
	s_mov_b32 m0, s2
	v_readfirstlane_b32 s2, v4
	v_lshl_add_u64 v[2:3], v[8:9], 0, s[12:13]
	s_mov_b32 m0, s2
	s_mov_b64 s[2:3], 0x60000
	v_add_u32_e32 v4, 0xc000, v109
	v_lshl_add_u64 v[2:3], v[8:9], 0, s[2:3]
	v_readfirstlane_b32 s2, v4
	s_mov_b32 m0, s2
	v_and_b32_e32 v102, 31, v100
	v_lshlrev_b32_e32 v105, 6, v11
	v_or_b32_e32 v3, v105, v102
	v_mul_i32_i24_e32 v106, 0x60, v10
	v_bfe_u32 v12, v100, 5, 1
	v_lshrrev_b32_e32 v104, 1, v100
	v_lshlrev_b32_e32 v112, 7, v3
	v_or_b32_e32 v3, v106, v102
	v_bfe_u32 v2, v100, 1, 3
	v_lshlrev_b32_e32 v113, 7, v3
	v_bitop3_b32 v3, v12, v104, 7 bitop3:0x78
	v_lshlrev_b32_e32 v111, 4, v3
	v_bitop3_b32 v3, v12, v2, 2 bitop3:0x36
	v_lshlrev_b32_e32 v110, 4, v3
	v_bitop3_b32 v3, v12, v2, 4 bitop3:0x36
	v_bitop3_b32 v2, v12, v2, 6 bitop3:0x36
	v_lshlrev_b32_e32 v107, 4, v2
	v_bitop3_b32 v2, v13, 7, v100 bitop3:0x48
	v_lshlrev_b32_e32 v2, 4, v2
	v_or_b32_e32 v6, v6, v2
	v_or_b32_e32 v0, v0, v2
	v_and_b32_e32 v101, 63, v100
	v_lshlrev_b32_e32 v108, 4, v3
	v_add_u32_e32 v114, 0x6000, v112
	v_lshl_add_u64 v[96:97], s[62:63], 0, v[6:7]
	v_lshl_add_u64 v[98:99], s[14:15], 0, v[0:1]
	s_mov_b32 s7, 0
	s_mov_b64 s[2:3], 0
	v_mov_b32_e32 v33, v32
	v_mov_b32_e32 v34, v32
	v_mov_b32_e32 v35, v32
	v_mov_b32_e32 v36, v32
	v_mov_b32_e32 v37, v32
	v_mov_b32_e32 v38, v32
	v_mov_b32_e32 v39, v32
	v_mov_b32_e32 v40, v32
	v_mov_b32_e32 v41, v32
	v_mov_b32_e32 v42, v32
	v_mov_b32_e32 v43, v32
	v_mov_b32_e32 v44, v32
	v_mov_b32_e32 v45, v32
	v_mov_b32_e32 v46, v32
	v_mov_b32_e32 v47, v32
	v_mov_b32_e32 v64, v32
	v_mov_b32_e32 v65, v32
	v_mov_b32_e32 v66, v32
	v_mov_b32_e32 v67, v32
	v_mov_b32_e32 v68, v32
	v_mov_b32_e32 v69, v32
	v_mov_b32_e32 v70, v32
	v_mov_b32_e32 v71, v32
	v_mov_b32_e32 v72, v32
	v_mov_b32_e32 v73, v32
	v_mov_b32_e32 v74, v32
	v_mov_b32_e32 v75, v32
	v_mov_b32_e32 v76, v32
	v_mov_b32_e32 v77, v32
	v_mov_b32_e32 v78, v32
	v_mov_b32_e32 v79, v32
	v_mov_b32_e32 v0, v32
	v_mov_b32_e32 v1, v32
	v_mov_b32_e32 v2, v32
	v_mov_b32_e32 v3, v32
	v_mov_b32_e32 v4, v32
	v_mov_b32_e32 v5, v32
	v_mov_b32_e32 v6, v32
	v_mov_b32_e32 v7, v32
	v_mov_b32_e32 v8, v32
	v_mov_b32_e32 v9, v32
	v_mov_b32_e32 v10, v32
	v_mov_b32_e32 v11, v32
	v_mov_b32_e32 v12, v32
	v_mov_b32_e32 v13, v32
	v_mov_b32_e32 v14, v32
	v_mov_b32_e32 v15, v32
	v_mov_b32_e32 v80, v32
	v_mov_b32_e32 v81, v32
	v_mov_b32_e32 v82, v32
	v_mov_b32_e32 v83, v32
	v_mov_b32_e32 v84, v32
	v_mov_b32_e32 v85, v32
	v_mov_b32_e32 v86, v32
	v_mov_b32_e32 v87, v32
	v_mov_b32_e32 v88, v32
	v_mov_b32_e32 v89, v32
	v_mov_b32_e32 v90, v32
	v_mov_b32_e32 v91, v32
	v_mov_b32_e32 v92, v32
	v_mov_b32_e32 v93, v32
	v_mov_b32_e32 v94, v32
	v_mov_b32_e32 v95, v32
	v_mov_b32_e32 v48, v32
	v_mov_b32_e32 v49, v32
	v_mov_b32_e32 v50, v32
	v_mov_b32_e32 v51, v32
	v_mov_b32_e32 v52, v32
	v_mov_b32_e32 v53, v32
	v_mov_b32_e32 v54, v32
	v_mov_b32_e32 v55, v32
	v_mov_b32_e32 v56, v32
	v_mov_b32_e32 v57, v32
	v_mov_b32_e32 v58, v32
	v_mov_b32_e32 v59, v32
	v_mov_b32_e32 v60, v32
	v_mov_b32_e32 v61, v32
	v_mov_b32_e32 v62, v32
	v_mov_b32_e32 v63, v32
	v_mov_b32_e32 v16, v32
	v_mov_b32_e32 v17, v32
	v_mov_b32_e32 v18, v32
	v_mov_b32_e32 v19, v32
	v_mov_b32_e32 v20, v32
	v_mov_b32_e32 v21, v32
	v_mov_b32_e32 v22, v32
	v_mov_b32_e32 v23, v32
	v_mov_b32_e32 v24, v32
	v_mov_b32_e32 v25, v32
	v_mov_b32_e32 v26, v32
	v_mov_b32_e32 v27, v32
	v_mov_b32_e32 v28, v32
	v_mov_b32_e32 v29, v32
	v_mov_b32_e32 v30, v32
	v_mov_b32_e32 v31, v32
	s_mov_b64 s[12:13], 0x8794080
	s_mov_b64 s[16:17], 0x87b4080
	s_mov_b64 s[18:19], 0x87d4080
	v_add_u32_e32 v243, s4, v106
	v_lshrrev_b32_e32 v244, 4, v101
	v_or_b32_e32 v243, v243, v244
	v_and_b32_e32 v244, 15, v100
	v_add_u32_e32 v245, s8, v105
	v_lshl_or_b32 v244, v244, 2, v245
	v_lshlrev_b32_e32 v243, 12, v243
	v_lshl_add_u32 v243, v244, 2, v243
	global_load_dwordx4 v[198:201], v243, s[40:41]
	v_add_u32_e32 v243, 0x4000, v243
	global_load_dwordx4 v[202:205], v243, s[40:41]
	v_add_u32_e32 v243, 0x4000, v243
	global_load_dwordx4 v[206:209], v243, s[40:41]
	v_add_u32_e32 v243, 0x4000, v243
	global_load_dwordx4 v[210:213], v243, s[40:41]
	v_add_u32_e32 v243, 0x4000, v243
	global_load_dwordx4 v[214:217], v243, s[40:41]
	v_add_u32_e32 v243, 0x4000, v243
	global_load_dwordx4 v[218:221], v243, s[40:41]
	v_add_u32_e32 v243, 0x4000, v243
	global_load_dwordx4 v[222:225], v243, s[40:41]
	v_add_u32_e32 v243, 0x4000, v243
	global_load_dwordx4 v[226:229], v243, s[40:41]
.LBB0_681:
	s_add_i32 s9, s7, 1
	s_bitcmp1_b32 s9, 0
	s_cselect_b32 s10, 0xe000, 0
	v_add_u32_e32 v115, s10, v109
	v_lshl_add_u64 v[116:117], v[98:99], 0, s[2:3]
	v_readfirstlane_b32 s10, v115
	v_add_u32_e32 v120, 0x2000, v115
	v_lshl_add_u64 v[118:119], v[116:117], 0, s[12:13]
	s_mov_b32 m0, s10
	v_readfirstlane_b32 s10, v120
	s_waitcnt vmcnt(0)
	s_waitcnt vmcnt(0) lgkmcnt(0)
	s_barrier
	global_load_lds_dwordx4 v[118:119], off
	v_lshl_add_u64 v[118:119], v[116:117], 0, s[16:17]
	s_mov_b32 m0, s10
	v_lshl_add_u64 v[116:117], v[116:117], 0, s[18:19]
	global_load_lds_dwordx4 v[118:119], off
	v_add_u32_e32 v118, 0x4000, v115
	v_add_u32_e32 v120, 0x6000, v115
	v_readfirstlane_b32 s10, v118
	s_mov_b32 m0, s10
	s_mov_b64 s[10:11], 0x6a94080
	global_load_lds_dwordx4 v[116:117], off
	v_lshl_add_u64 v[116:117], v[96:97], 0, s[2:3]
	v_lshl_add_u64 v[118:119], v[116:117], 0, s[10:11]
	v_readfirstlane_b32 s10, v120
	s_mov_b32 m0, s10
	s_mov_b64 s[10:11], 0x6ab4080
	v_add_u32_e32 v120, 0x8000, v115
	global_load_lds_dwordx4 v[118:119], off
	v_lshl_add_u64 v[118:119], v[116:117], 0, s[10:11]
	v_readfirstlane_b32 s10, v120
	s_mov_b32 m0, s10
	s_mov_b64 s[10:11], 0x6ad4080
	v_add_u32_e32 v120, 0xa000, v115
	global_load_lds_dwordx4 v[118:119], off
	v_lshl_add_u64 v[118:119], v[116:117], 0, s[10:11]
	v_readfirstlane_b32 s10, v120
	s_mov_b32 m0, s10
	s_mov_b64 s[10:11], 0x6af4080
	v_add_u32_e32 v115, 0xc000, v115
	v_lshl_add_u64 v[116:117], v[116:117], 0, s[10:11]
	v_readfirstlane_b32 s10, v115
	global_load_lds_dwordx4 v[118:119], off
	s_mov_b32 m0, s10
	s_nop 0
	global_load_lds_dwordx4 v[116:117], off
	s_bitcmp1_b32 s7, 0
	s_cselect_b32 s7, 0xe000, 0
	v_add_u32_e32 v115, s7, v114
	v_add_u32_e32 v120, v115, v111
	ds_read_b128 v[116:119], v120 offset:0
	v_add_u32_e32 v128, s7, v113
	ds_read_b128 v[120:123], v120 offset:0x1000
	v_add_u32_e32 v134, v128, v111
	ds_read_b128 v[124:127], v134 offset:0
	ds_read_b128 v[130:133], v134 offset:0x1000
	ds_read_b128 v[134:137], v134 offset:0x2000
	v_add_u32_e32 v148, v115, v110
	ds_read_b128 v[144:147], v148 offset:0
	ds_read_b128 v[148:151], v148 offset:0x1000
	v_add_u32_e32 v152, v128, v110
	ds_read_b128 v[182:185], v152 offset:0
	ds_read_b128 v[186:189], v152 offset:0x1000
	ds_read_b128 v[190:193], v152 offset:0x2000
	s_waitcnt lgkmcnt(5)
	s_nop 0
	v_mfma_f32_32x32x16_bf16 v[64:79], v[116:119], v[124:127], v[64:79]
	v_mfma_f32_32x32x16_bf16 v[32:47], v[116:119], v[130:133], v[32:47]
	v_mfma_f32_32x32x16_bf16 v[0:15], v[116:119], v[134:137], v[0:15]
	v_mfma_f32_32x32x16_bf16 v[80:95], v[120:123], v[124:127], v[80:95]
	v_mfma_f32_32x32x16_bf16 v[48:63], v[120:123], v[130:133], v[48:63]
	v_mfma_f32_32x32x16_bf16 v[16:31], v[120:123], v[134:137], v[16:31]
	v_add_u32_e32 v120, v115, v108
	ds_read_b128 v[116:119], v120 offset:0
	ds_read_b128 v[120:123], v120 offset:0x1000
	v_add_u32_e32 v134, v128, v108
	ds_read_b128 v[124:127], v134 offset:0
	ds_read_b128 v[130:133], v134 offset:0x1000
	ds_read_b128 v[134:137], v134 offset:0x2000
	s_waitcnt lgkmcnt(5)
	s_nop 0
	v_mfma_f32_32x32x16_bf16 v[64:79], v[144:147], v[182:185], v[64:79]
	v_mfma_f32_32x32x16_bf16 v[32:47], v[144:147], v[186:189], v[32:47]
	v_mfma_f32_32x32x16_bf16 v[0:15], v[144:147], v[190:193], v[0:15]
	v_mfma_f32_32x32x16_bf16 v[80:95], v[148:151], v[182:185], v[80:95]
	v_mfma_f32_32x32x16_bf16 v[48:63], v[148:151], v[186:189], v[48:63]
	v_mfma_f32_32x32x16_bf16 v[16:31], v[148:151], v[190:193], v[16:31]
	v_add_u32_e32 v115, v115, v107
	ds_read_b128 v[144:147], v115 offset:0
	ds_read_b128 v[148:151], v115 offset:0x1000
	v_add_u32_e32 v115, v128, v107
	ds_read_b128 v[182:185], v115 offset:0
	ds_read_b128 v[186:189], v115 offset:0x1000
	ds_read_b128 v[190:193], v115 offset:0x2000
	s_waitcnt lgkmcnt(5)
	s_nop 0
	v_mfma_f32_32x32x16_bf16 v[64:79], v[116:119], v[124:127], v[64:79]
	v_mfma_f32_32x32x16_bf16 v[32:47], v[116:119], v[130:133], v[32:47]
	v_mfma_f32_32x32x16_bf16 v[0:15], v[116:119], v[134:137], v[0:15]
	v_mfma_f32_32x32x16_bf16 v[80:95], v[120:123], v[124:127], v[80:95]
	v_mfma_f32_32x32x16_bf16 v[48:63], v[120:123], v[130:133], v[48:63]
	v_mfma_f32_32x32x16_bf16 v[16:31], v[120:123], v[134:137], v[16:31]
	s_waitcnt lgkmcnt(0)
	s_nop 0
	v_mfma_f32_32x32x16_bf16 v[64:79], v[144:147], v[182:185], v[64:79]
	v_mfma_f32_32x32x16_bf16 v[32:47], v[144:147], v[186:189], v[32:47]
	v_mfma_f32_32x32x16_bf16 v[0:15], v[144:147], v[190:193], v[0:15]
	v_mfma_f32_32x32x16_bf16 v[80:95], v[148:151], v[182:185], v[80:95]
	v_mfma_f32_32x32x16_bf16 v[48:63], v[148:151], v[186:189], v[48:63]
	v_mfma_f32_32x32x16_bf16 v[16:31], v[148:151], v[190:193], v[16:31]
	s_add_u32 s2, s2, 0x80
	s_addc_u32 s3, s3, 0
	s_cmpk_eq_i32 s2, 0x780
	s_mov_b32 s7, s9
	s_cbranch_scc0 .LBB0_681
	s_waitcnt vmcnt(0)
	s_waitcnt vmcnt(0) lgkmcnt(0)
	s_barrier
	v_add_u32_e32 v109, 0x14000, v112
	v_add_u32_e32 v112, v109, v111
	ds_read_b128 v[96:99], v112 offset:0
	v_add_u32_e32 v128, 0xe000, v113
	ds_read_b128 v[112:115], v112 offset:0x1000
	v_add_u32_e32 v111, v128, v111
	ds_read_b128 v[116:119], v111 offset:0
	ds_read_b128 v[120:123], v111 offset:0x1000
	ds_read_b128 v[124:127], v111 offset:0x2000
	v_add_u32_e32 v111, v109, v110
	ds_read_b128 v[130:133], v111 offset:0
	ds_read_b128 v[134:137], v111 offset:0x1000
	v_add_u32_e32 v110, v128, v110
	ds_read_b128 v[144:147], v110 offset:0
	ds_read_b128 v[148:151], v110 offset:0x1000
	ds_read_b128 v[182:185], v110 offset:0x2000
	s_waitcnt lgkmcnt(5)
	s_nop 0
	v_mfma_f32_32x32x16_bf16 v[64:79], v[96:99], v[116:119], v[64:79]
	v_mfma_f32_32x32x16_bf16 v[32:47], v[96:99], v[120:123], v[32:47]
	v_mfma_f32_32x32x16_bf16 v[0:15], v[96:99], v[124:127], v[0:15]
	v_mfma_f32_32x32x16_bf16 v[48:63], v[112:115], v[120:123], v[48:63]
	v_mfma_f32_32x32x16_bf16 v[16:31], v[112:115], v[124:127], v[16:31]
	v_mfma_f32_32x32x16_bf16 v[80:95], v[112:115], v[116:119], v[80:95]
	v_add_u32_e32 v110, v109, v108
	ds_read_b128 v[96:99], v110 offset:0
	ds_read_b128 v[110:113], v110 offset:0x1000
	v_add_u32_e32 v108, v128, v108
	ds_read_b128 v[114:117], v108 offset:0
	ds_read_b128 v[118:121], v108 offset:0x1000
	ds_read_b128 v[122:125], v108 offset:0x2000
	s_waitcnt lgkmcnt(5)
	s_nop 0
	v_mfma_f32_32x32x16_bf16 v[64:79], v[130:133], v[144:147], v[64:79]
	v_mfma_f32_32x32x16_bf16 v[32:47], v[130:133], v[148:151], v[32:47]
	v_mfma_f32_32x32x16_bf16 v[0:15], v[130:133], v[182:185], v[0:15]
	v_mfma_f32_32x32x16_bf16 v[48:63], v[134:137], v[148:151], v[48:63]
	v_mfma_f32_32x32x16_bf16 v[16:31], v[134:137], v[182:185], v[16:31]
	v_mfma_f32_32x32x16_bf16 v[80:95], v[134:137], v[144:147], v[80:95]
	v_add_u32_e32 v108, v109, v107
	ds_read_b128 v[130:133], v108 offset:0
	ds_read_b128 v[134:137], v108 offset:0x1000
	v_add_u32_e32 v107, v128, v107
	ds_read_b128 v[144:147], v107 offset:0
	ds_read_b128 v[148:151], v107 offset:0x1000
	ds_read_b128 v[182:185], v107 offset:0x2000
	s_waitcnt lgkmcnt(5)
	s_nop 0
	v_mfma_f32_32x32x16_bf16 v[64:79], v[96:99], v[114:117], v[64:79]
	v_mfma_f32_32x32x16_bf16 v[32:47], v[96:99], v[118:121], v[32:47]
	v_mfma_f32_32x32x16_bf16 v[0:15], v[96:99], v[122:125], v[0:15]
	v_mfma_f32_32x32x16_bf16 v[48:63], v[110:113], v[118:121], v[48:63]
	v_mfma_f32_32x32x16_bf16 v[16:31], v[110:113], v[122:125], v[16:31]
	v_mfma_f32_32x32x16_bf16 v[80:95], v[110:113], v[114:117], v[80:95]
	s_waitcnt lgkmcnt(0)
	s_nop 0
	v_mfma_f32_32x32x16_bf16 v[64:79], v[130:133], v[144:147], v[64:79]
	v_mfma_f32_32x32x16_bf16 v[32:47], v[130:133], v[148:151], v[32:47]
	v_mfma_f32_32x32x16_bf16 v[0:15], v[130:133], v[182:185], v[0:15]
	v_mfma_f32_32x32x16_bf16 v[48:63], v[134:137], v[148:151], v[48:63]
	v_mfma_f32_32x32x16_bf16 v[16:31], v[134:137], v[182:185], v[16:31]
	v_mfma_f32_32x32x16_bf16 v[80:95], v[134:137], v[144:147], v[80:95]
	v_add_u32_e32 v96, s4, v106
	v_lshrrev_b32_e32 v128, 4, v101
	v_and_b32_e32 v112, 15, v100
	v_or_b32_e32 v100, v96, v128
	v_add_u32_e32 v105, s8, v105
	v_ashrrev_i32_e32 v101, 31, v100
	v_lshl_or_b32 v98, v112, 2, v105
	v_lshlrev_b64 v[106:107], 12, v[100:101]
	v_ashrrev_i32_e32 v99, 31, v98
	v_lshl_add_u64 v[106:107], s[40:41], 0, v[106:107]
	v_lshl_add_u64 v[110:111], v[98:99], 2, v[106:107]
	s_barrier
	v_add_co_u32_e32 v182, vcc, 0x20000, v110
	s_nop 1
	v_addc_co_u32_e32 v183, vcc, 0, v111, vcc
	global_load_dwordx4 v[184:187], v[182:183], off
	v_add_co_u32_e32 v182, vcc, 0x4000, v182
	s_nop 1
	v_addc_co_u32_e32 v183, vcc, 0, v183, vcc
	global_load_dwordx4 v[188:191], v[182:183], off
	v_add_co_u32_e32 v182, vcc, 0x4000, v182
	s_nop 1
	v_addc_co_u32_e32 v183, vcc, 0, v183, vcc
	global_load_dwordx4 v[192:195], v[182:183], off
	v_add_co_u32_e32 v182, vcc, 0x4000, v182
	s_nop 1
	v_addc_co_u32_e32 v183, vcc, 0, v183, vcc
	global_load_dwordx4 v[116:119], v[182:183], off
	v_add_co_u32_e32 v182, vcc, 0x4000, v182
	s_nop 1
	v_addc_co_u32_e32 v183, vcc, 0, v183, vcc
	global_load_dwordx4 v[120:123], v[182:183], off
	v_add_co_u32_e32 v182, vcc, 0x4000, v182
	s_nop 1
	v_addc_co_u32_e32 v183, vcc, 0, v183, vcc
	global_load_dwordx4 v[124:127], v[182:183], off
	v_add_co_u32_e32 v182, vcc, 0x4000, v182
	s_nop 1
	v_addc_co_u32_e32 v183, vcc, 0, v183, vcc
	global_load_dwordx4 v[130:133], v[182:183], off
	v_add_co_u32_e32 v182, vcc, 0x4000, v182
	s_nop 1
	v_addc_co_u32_e32 v183, vcc, 0, v183, vcc
	global_load_dwordx4 v[134:137], v[182:183], off
	s_movk_i32 s2, 0x2400
	s_cmp_lt_i32 s5, 22
	v_mul_lo_u32 v97, v103, s2
	s_cselect_b64 s[2:3], -1, 0
	s_cmp_gt_i32 s5, 21
	s_movk_i32 s5, 0x110
	v_and_b32_e32 v103, 16, v104
	v_mad_u32_u24 v104, v102, s5, v97
	v_add_u32_e32 v113, 0xfffff000, v96
	v_cndmask_b32_e64 v102, 0, 1, s[2:3]
	s_cselect_b64 s[2:3], -1, 0
	s_add_i32 s7, s4, 0xfffff000
	v_add_u32_e32 v104, v104, v103
	ds_write_b128 v104, v[64:67]
	ds_write_b128 v104, v[68:71] offset:32
	ds_write_b128 v104, v[72:75] offset:64
	ds_write_b128 v104, v[76:79] offset:96
	ds_write_b128 v104, v[80:83] offset:128
	ds_write_b128 v104, v[84:87] offset:160
	ds_write_b128 v104, v[88:91] offset:192
	ds_write_b128 v104, v[92:95] offset:224
	v_xor_b32_e32 v64, s7, v113
	s_movk_i32 s4, 0x400
	v_lshl_or_b32 v97, v112, 4, v97
	v_cmp_gt_u32_e32 vcc, s4, v64
	v_mad_u32_u24 v115, v128, s5, v97
	s_and_b64 s[4:5], s[2:3], vcc
	v_cndmask_b32_e64 v71, 0, 1, s[4:5]
	s_movk_i32 s4, 0x1000
	v_cmp_gt_i32_e32 vcc, s4, v100
	v_subrev_u32_e32 v114, s8, v98
	v_lshl_add_u32 v103, v114, 2, v167
	v_cndmask_b32_e32 v64, v71, v102, vcc
	v_and_b32_e32 v64, 1, v64
	v_cmp_eq_u32_e32 vcc, 1, v64
	v_ashrrev_i32_e32 v68, 6, v105
	s_mov_b32 s4, 0xc000
	v_cndmask_b32_e64 v64, v171, 0, vcc
	v_add_u32_e32 v70, v103, v64
	ds_read_b128 v[64:67], v115
	ds_read_b128 v[72:75], v70
	v_cmp_eq_u32_e64 s[36:37], 0, v112
	v_mad_i64_i32 v[68:69], s[4:5], v68, s4, 0
	s_and_b64 vcc, exec, s[0:1]
	s_waitcnt lgkmcnt(0)
	v_pk_fma_f32 v[66:67], v[66:67], v[74:75], v[200:201]
	v_pk_fma_f32 v[64:65], v[64:65], v[72:73], v[198:199]
	global_store_dwordx4 v[110:111], v[64:67], off
	s_cbranch_vccnz .LBB0_686
	ds_read_b128 v[72:75], v70 offset:2048
	v_lshlrev_b64 v[76:77], 10, v[100:101]
	v_lshl_add_u64 v[76:77], v[76:77], 1, s[42:43]
	v_lshl_add_u64 v[76:77], v[98:99], 1, v[76:77]
	s_waitcnt lgkmcnt(0)
	v_pk_mul_f32 v[72:73], v[64:65], v[72:73]
	v_pk_mul_f32 v[64:65], v[64:65], v[64:65]
	v_pk_mul_f32 v[74:75], v[66:67], v[74:75]
	v_pk_mul_f32 v[66:67], v[66:67], v[66:67]
	v_add_f32_e32 v64, v64, v65
	v_add_f32_e32 v64, v66, v64
	v_add_f32_e32 v64, v67, v64
	v_cvt_pk_bf16_f32 v72, v72, v73
	v_cvt_pk_bf16_f32 v73, v74, v75
	v_add_f32_dpp v64, v64, v64 quad_perm:[1,0,3,2] row_mask:0xf bank_mask:0xf bound_ctrl:1
	global_store_dwordx2 v[76:77], v[72:73], off
	s_nop 0
	v_add_f32_dpp v64, v64, v64 quad_perm:[2,3,0,1] row_mask:0xf bank_mask:0xf bound_ctrl:1
	s_nop 1
	v_add_f32_dpp v64, v64, v64 row_half_mirror row_mask:0xf bank_mask:0xf bound_ctrl:1
	s_nop 1
	v_mov_b32_dpp v65, v64 row_mirror row_mask:0xf bank_mask:0xf bound_ctrl:1
	s_and_saveexec_b64 s[4:5], s[36:37]
	s_cbranch_execz .LBB0_685
	v_lshl_add_u64 v[66:67], s[52:53], 0, v[68:69]
	v_lshl_add_u64 v[66:67], v[100:101], 2, v[66:67]
	v_add_f32_e32 v64, v64, v65
	global_store_dword v[66:67], v64, off

.LBB0_686:
	v_or_b32_e32 v70, 4, v128
	v_or_b32_e32 v72, v96, v70
	v_ashrrev_i32_e32 v73, 31, v72
	v_lshlrev_b64 v[64:65], 12, v[72:73]
	v_lshl_add_u64 v[64:65], s[40:41], 0, v[64:65]
	v_lshl_add_u64 v[84:85], v[98:99], 2, v[64:65]
	s_movk_i32 s4, 0x1000
	v_mul_u32_u24_e32 v74, 0x110, v128
	v_cmp_gt_i32_e32 vcc, s4, v72
	v_add_u32_e32 v86, v74, v97
	s_nop 0
	v_cndmask_b32_e32 v74, v71, v102, vcc
	v_and_b32_e32 v74, 1, v74
	v_cmp_eq_u32_e32 vcc, 1, v74
	s_nop 1
	v_cndmask_b32_e64 v74, v171, 0, vcc
	v_add_u32_e32 v74, v103, v74
	ds_read_b128 v[76:79], v86 offset:1088
	ds_read_b128 v[80:83], v74
	s_and_b64 vcc, exec, s[0:1]
	s_waitcnt lgkmcnt(0)
	v_pk_fma_f32 v[66:67], v[78:79], v[82:83], v[204:205]
	v_pk_fma_f32 v[64:65], v[76:77], v[80:81], v[202:203]
	global_store_dwordx4 v[84:85], v[64:67], off
	s_cbranch_vccnz .LBB0_690
	ds_read_b128 v[74:77], v74 offset:2048
	v_lshlrev_b64 v[72:73], 10, v[72:73]
	v_lshl_add_u64 v[72:73], v[72:73], 1, s[42:43]
	v_lshl_add_u64 v[72:73], v[98:99], 1, v[72:73]
	s_waitcnt lgkmcnt(0)
	v_pk_mul_f32 v[74:75], v[64:65], v[74:75]
	v_pk_mul_f32 v[64:65], v[64:65], v[64:65]
	v_pk_mul_f32 v[76:77], v[66:67], v[76:77]
	v_pk_mul_f32 v[66:67], v[66:67], v[66:67]
	v_add_f32_e32 v64, v64, v65
	v_add_f32_e32 v64, v66, v64
	v_add_f32_e32 v64, v67, v64
	v_cvt_pk_bf16_f32 v74, v74, v75
	v_cvt_pk_bf16_f32 v75, v76, v77
	v_add_f32_dpp v64, v64, v64 quad_perm:[1,0,3,2] row_mask:0xf bank_mask:0xf bound_ctrl:1
	global_store_dwordx2 v[72:73], v[74:75], off
	s_nop 0
	v_add_f32_dpp v64, v64, v64 quad_perm:[2,3,0,1] row_mask:0xf bank_mask:0xf bound_ctrl:1
	s_nop 1
	v_add_f32_dpp v64, v64, v64 row_half_mirror row_mask:0xf bank_mask:0xf bound_ctrl:1
	s_nop 1
	v_mov_b32_dpp v65, v64 row_mirror row_mask:0xf bank_mask:0xf bound_ctrl:1
	s_and_saveexec_b64 s[4:5], s[36:37]
	s_cbranch_execz .LBB0_689
	v_ashrrev_i32_e32 v97, 31, v96
	v_lshl_add_u64 v[66:67], s[52:53], 0, v[68:69]
	v_lshl_add_u64 v[72:73], v[96:97], 0, v[128:129]
	v_lshl_add_u64 v[66:67], v[72:73], 2, v[66:67]
	v_add_f32_e32 v64, v64, v65
	global_store_dword v[66:67], v64, off offset:16

.LBB0_690:
	v_or_b32_e32 v72, 8, v128
	v_or_b32_e32 v74, v96, v72
	v_ashrrev_i32_e32 v75, 31, v74
	v_lshlrev_b64 v[64:65], 12, v[74:75]
	v_lshl_add_u64 v[64:65], s[40:41], 0, v[64:65]
	v_lshl_add_u64 v[84:85], v[98:99], 2, v[64:65]
	s_movk_i32 s4, 0x1000
	v_cmp_gt_i32_e32 vcc, s4, v74
	s_nop 1
	v_cndmask_b32_e32 v73, v71, v102, vcc
	v_and_b32_e32 v73, 1, v73
	v_cmp_eq_u32_e32 vcc, 1, v73
	s_nop 1
	v_cndmask_b32_e64 v73, v171, 0, vcc
	v_add_u32_e32 v73, v103, v73
	ds_read_b128 v[76:79], v86 offset:2176
	ds_read_b128 v[80:83], v73
	s_and_b64 vcc, exec, s[0:1]
	s_waitcnt lgkmcnt(0)
	v_pk_fma_f32 v[66:67], v[78:79], v[82:83], v[208:209]
	v_pk_fma_f32 v[64:65], v[76:77], v[80:81], v[206:207]
	global_store_dwordx4 v[84:85], v[64:67], off
	s_cbranch_vccnz .LBB0_694
	ds_read_b128 v[76:79], v73 offset:2048
	v_lshlrev_b64 v[74:75], 10, v[74:75]
	v_lshl_add_u64 v[74:75], v[74:75], 1, s[42:43]
	v_lshl_add_u64 v[74:75], v[98:99], 1, v[74:75]
	s_waitcnt lgkmcnt(0)
	v_pk_mul_f32 v[76:77], v[64:65], v[76:77]
	v_pk_mul_f32 v[64:65], v[64:65], v[64:65]
	v_pk_mul_f32 v[78:79], v[66:67], v[78:79]
	v_pk_mul_f32 v[66:67], v[66:67], v[66:67]
	v_add_f32_e32 v64, v64, v65
	v_add_f32_e32 v64, v66, v64
	v_add_f32_e32 v64, v67, v64
	v_cvt_pk_bf16_f32 v76, v76, v77
	v_cvt_pk_bf16_f32 v77, v78, v79
	v_add_f32_dpp v64, v64, v64 quad_perm:[1,0,3,2] row_mask:0xf bank_mask:0xf bound_ctrl:1
	global_store_dwordx2 v[74:75], v[76:77], off
	s_nop 0
	v_add_f32_dpp v64, v64, v64 quad_perm:[2,3,0,1] row_mask:0xf bank_mask:0xf bound_ctrl:1
	s_nop 1
	v_add_f32_dpp v64, v64, v64 row_half_mirror row_mask:0xf bank_mask:0xf bound_ctrl:1
	s_nop 1
	v_mov_b32_dpp v65, v64 row_mirror row_mask:0xf bank_mask:0xf bound_ctrl:1
	s_and_saveexec_b64 s[4:5], s[36:37]
	s_cbranch_execz .LBB0_693
	v_ashrrev_i32_e32 v97, 31, v96
	v_lshl_add_u64 v[66:67], s[52:53], 0, v[68:69]
	v_lshl_add_u64 v[74:75], v[96:97], 0, v[128:129]
	v_lshl_add_u64 v[66:67], v[74:75], 2, v[66:67]
	v_add_f32_e32 v64, v64, v65
	global_store_dword v[66:67], v64, off offset:32

.LBB0_694:
	v_or_b32_e32 v74, 12, v128
	v_or_b32_e32 v76, v96, v74
	v_ashrrev_i32_e32 v77, 31, v76
	v_lshlrev_b64 v[64:65], 12, v[76:77]
	v_lshl_add_u64 v[64:65], s[40:41], 0, v[64:65]
	v_lshl_add_u64 v[88:89], v[98:99], 2, v[64:65]
	s_movk_i32 s4, 0x1000
	v_cmp_gt_i32_e32 vcc, s4, v76
	s_nop 1
	v_cndmask_b32_e32 v73, v71, v102, vcc
	v_and_b32_e32 v73, 1, v73
	v_cmp_eq_u32_e32 vcc, 1, v73
	s_nop 1
	v_cndmask_b32_e64 v73, v171, 0, vcc
	v_add_u32_e32 v73, v103, v73
	ds_read_b128 v[78:81], v86 offset:3264
	ds_read_b128 v[82:85], v73
	s_and_b64 vcc, exec, s[0:1]
	s_waitcnt lgkmcnt(0)
	v_pk_fma_f32 v[66:67], v[80:81], v[84:85], v[212:213]
	v_pk_fma_f32 v[64:65], v[78:79], v[82:83], v[210:211]
	global_store_dwordx4 v[88:89], v[64:67], off
	s_cbranch_vccnz .LBB0_698
	ds_read_b128 v[78:81], v73 offset:2048
	v_lshlrev_b64 v[76:77], 10, v[76:77]
	v_lshl_add_u64 v[76:77], v[76:77], 1, s[42:43]
	v_lshl_add_u64 v[76:77], v[98:99], 1, v[76:77]
	s_waitcnt lgkmcnt(0)
	v_pk_mul_f32 v[78:79], v[64:65], v[78:79]
	v_pk_mul_f32 v[64:65], v[64:65], v[64:65]
	v_pk_mul_f32 v[80:81], v[66:67], v[80:81]
	v_pk_mul_f32 v[66:67], v[66:67], v[66:67]
	v_add_f32_e32 v64, v64, v65
	v_add_f32_e32 v64, v66, v64
	v_add_f32_e32 v64, v67, v64
	v_cvt_pk_bf16_f32 v78, v78, v79
	v_cvt_pk_bf16_f32 v79, v80, v81
	v_add_f32_dpp v64, v64, v64 quad_perm:[1,0,3,2] row_mask:0xf bank_mask:0xf bound_ctrl:1
	global_store_dwordx2 v[76:77], v[78:79], off
	s_nop 0
	v_add_f32_dpp v64, v64, v64 quad_perm:[2,3,0,1] row_mask:0xf bank_mask:0xf bound_ctrl:1
	s_nop 1
	v_add_f32_dpp v64, v64, v64 row_half_mirror row_mask:0xf bank_mask:0xf bound_ctrl:1
	s_nop 1
	v_mov_b32_dpp v65, v64 row_mirror row_mask:0xf bank_mask:0xf bound_ctrl:1
	s_and_saveexec_b64 s[4:5], s[36:37]
	s_cbranch_execz .LBB0_697
	v_ashrrev_i32_e32 v97, 31, v96
	v_lshl_add_u64 v[66:67], s[52:53], 0, v[68:69]
	v_lshl_add_u64 v[76:77], v[96:97], 0, v[128:129]
	v_lshl_add_u64 v[66:67], v[76:77], 2, v[66:67]
	v_add_f32_e32 v64, v64, v65
	global_store_dword v[66:67], v64, off offset:48

.LBB0_698:
	v_or_b32_e32 v76, 16, v128
	v_or_b32_e32 v78, v96, v76
	v_ashrrev_i32_e32 v79, 31, v78
	v_lshlrev_b64 v[64:65], 12, v[78:79]
	v_lshl_add_u64 v[64:65], s[40:41], 0, v[64:65]
	v_lshl_add_u64 v[84:85], v[98:99], 2, v[64:65]
	s_movk_i32 s4, 0x1000
	v_cmp_gt_i32_e32 vcc, s4, v78
	s_nop 1
	v_cndmask_b32_e32 v73, v71, v102, vcc
	v_and_b32_e32 v73, 1, v73
	v_cmp_eq_u32_e32 vcc, 1, v73
	s_nop 1
	v_cndmask_b32_e64 v73, v171, 0, vcc
	v_add_u32_e32 v73, v103, v73
	ds_read_b128 v[80:83], v86 offset:4352
	ds_read_b128 v[88:91], v73
	s_and_b64 vcc, exec, s[0:1]
	s_waitcnt lgkmcnt(0)
	v_pk_fma_f32 v[66:67], v[82:83], v[90:91], v[216:217]
	v_pk_fma_f32 v[64:65], v[80:81], v[88:89], v[214:215]
	global_store_dwordx4 v[84:85], v[64:67], off
	s_cbranch_vccnz .LBB0_702
	ds_read_b128 v[80:83], v73 offset:2048
	v_lshlrev_b64 v[78:79], 10, v[78:79]
	v_lshl_add_u64 v[78:79], v[78:79], 1, s[42:43]
	v_lshl_add_u64 v[78:79], v[98:99], 1, v[78:79]
	s_waitcnt lgkmcnt(0)
	v_pk_mul_f32 v[80:81], v[64:65], v[80:81]
	v_pk_mul_f32 v[64:65], v[64:65], v[64:65]
	v_pk_mul_f32 v[82:83], v[66:67], v[82:83]
	v_pk_mul_f32 v[66:67], v[66:67], v[66:67]
	v_add_f32_e32 v64, v64, v65
	v_add_f32_e32 v64, v66, v64
	v_add_f32_e32 v64, v67, v64
	v_cvt_pk_bf16_f32 v80, v80, v81
	v_cvt_pk_bf16_f32 v81, v82, v83
	v_add_f32_dpp v64, v64, v64 quad_perm:[1,0,3,2] row_mask:0xf bank_mask:0xf bound_ctrl:1
	global_store_dwordx2 v[78:79], v[80:81], off
	s_nop 0
	v_add_f32_dpp v64, v64, v64 quad_perm:[2,3,0,1] row_mask:0xf bank_mask:0xf bound_ctrl:1
	s_nop 1
	v_add_f32_dpp v64, v64, v64 row_half_mirror row_mask:0xf bank_mask:0xf bound_ctrl:1
	s_nop 1
	v_mov_b32_dpp v65, v64 row_mirror row_mask:0xf bank_mask:0xf bound_ctrl:1
	s_and_saveexec_b64 s[4:5], s[36:37]
	s_cbranch_execz .LBB0_701
	v_ashrrev_i32_e32 v97, 31, v96
	v_lshl_add_u64 v[66:67], s[52:53], 0, v[68:69]
	v_lshl_add_u64 v[78:79], v[96:97], 0, v[128:129]
	v_lshl_add_u64 v[66:67], v[78:79], 2, v[66:67]
	v_add_f32_e32 v64, v64, v65
	global_store_dword v[66:67], v64, off offset:64

.LBB0_702:
	v_or_b32_e32 v78, 20, v128
	v_or_b32_e32 v80, v96, v78
	v_ashrrev_i32_e32 v81, 31, v80
	v_lshlrev_b64 v[64:65], 12, v[80:81]
	v_lshl_add_u64 v[64:65], s[40:41], 0, v[64:65]
	v_lshl_add_u64 v[92:93], v[98:99], 2, v[64:65]
	s_movk_i32 s4, 0x1000
	v_cmp_gt_i32_e32 vcc, s4, v80
	s_nop 1
	v_cndmask_b32_e32 v73, v71, v102, vcc
	v_and_b32_e32 v73, 1, v73
	v_cmp_eq_u32_e32 vcc, 1, v73
	s_nop 1
	v_cndmask_b32_e64 v73, v171, 0, vcc
	v_add_u32_e32 v73, v103, v73
	ds_read_b128 v[82:85], v86 offset:5440
	ds_read_b128 v[88:91], v73
	s_and_b64 vcc, exec, s[0:1]
	s_waitcnt lgkmcnt(0)
	v_pk_fma_f32 v[66:67], v[84:85], v[90:91], v[220:221]
	v_pk_fma_f32 v[64:65], v[82:83], v[88:89], v[218:219]
	global_store_dwordx4 v[92:93], v[64:67], off
	s_cbranch_vccnz .LBB0_706
	ds_read_b128 v[82:85], v73 offset:2048
	v_lshlrev_b64 v[80:81], 10, v[80:81]
	v_lshl_add_u64 v[80:81], v[80:81], 1, s[42:43]
	v_lshl_add_u64 v[80:81], v[98:99], 1, v[80:81]
	s_waitcnt lgkmcnt(0)
	v_pk_mul_f32 v[82:83], v[64:65], v[82:83]
	v_pk_mul_f32 v[64:65], v[64:65], v[64:65]
	v_pk_mul_f32 v[84:85], v[66:67], v[84:85]
	v_pk_mul_f32 v[66:67], v[66:67], v[66:67]
	v_add_f32_e32 v64, v64, v65
	v_add_f32_e32 v64, v66, v64
	v_add_f32_e32 v64, v67, v64
	v_cvt_pk_bf16_f32 v82, v82, v83
	v_cvt_pk_bf16_f32 v83, v84, v85
	v_add_f32_dpp v64, v64, v64 quad_perm:[1,0,3,2] row_mask:0xf bank_mask:0xf bound_ctrl:1
	global_store_dwordx2 v[80:81], v[82:83], off
	s_nop 0
	v_add_f32_dpp v64, v64, v64 quad_perm:[2,3,0,1] row_mask:0xf bank_mask:0xf bound_ctrl:1
	s_nop 1
	v_add_f32_dpp v64, v64, v64 row_half_mirror row_mask:0xf bank_mask:0xf bound_ctrl:1
	s_nop 1
	v_mov_b32_dpp v65, v64 row_mirror row_mask:0xf bank_mask:0xf bound_ctrl:1
	s_and_saveexec_b64 s[4:5], s[36:37]
	s_cbranch_execz .LBB0_705
	v_ashrrev_i32_e32 v97, 31, v96
	v_lshl_add_u64 v[66:67], s[52:53], 0, v[68:69]
	v_lshl_add_u64 v[80:81], v[96:97], 0, v[128:129]
	v_lshl_add_u64 v[66:67], v[80:81], 2, v[66:67]
	v_add_f32_e32 v64, v64, v65
	global_store_dword v[66:67], v64, off offset:80

.LBB0_706:
	v_or_b32_e32 v80, 24, v128
	v_or_b32_e32 v82, v96, v80
	v_ashrrev_i32_e32 v83, 31, v82
	v_lshlrev_b64 v[64:65], 12, v[82:83]
	v_lshl_add_u64 v[64:65], s[40:41], 0, v[64:65]
	v_lshl_add_u64 v[84:85], v[98:99], 2, v[64:65]
	s_movk_i32 s4, 0x1000
	v_cmp_gt_i32_e32 vcc, s4, v82
	s_nop 1
	v_cndmask_b32_e32 v73, v71, v102, vcc
	v_and_b32_e32 v73, 1, v73
	v_cmp_eq_u32_e32 vcc, 1, v73
	s_nop 1
	v_cndmask_b32_e64 v73, v171, 0, vcc
	v_add_u32_e32 v73, v103, v73
	ds_read_b128 v[88:91], v86 offset:6528
	ds_read_b128 v[92:95], v73
	s_and_b64 vcc, exec, s[0:1]
	s_waitcnt lgkmcnt(0)
	v_pk_fma_f32 v[66:67], v[90:91], v[94:95], v[224:225]
	v_pk_fma_f32 v[64:65], v[88:89], v[92:93], v[222:223]
	global_store_dwordx4 v[84:85], v[64:67], off
	s_cbranch_vccnz .LBB0_710
	ds_read_b128 v[88:91], v73 offset:2048
	v_lshlrev_b64 v[82:83], 10, v[82:83]
	v_lshl_add_u64 v[82:83], v[82:83], 1, s[42:43]
	v_lshl_add_u64 v[82:83], v[98:99], 1, v[82:83]
	s_waitcnt lgkmcnt(0)
	v_pk_mul_f32 v[88:89], v[64:65], v[88:89]
	v_pk_mul_f32 v[64:65], v[64:65], v[64:65]
	v_pk_mul_f32 v[84:85], v[66:67], v[90:91]
	v_pk_mul_f32 v[66:67], v[66:67], v[66:67]
	v_add_f32_e32 v64, v64, v65
	v_add_f32_e32 v64, v66, v64
	v_add_f32_e32 v64, v67, v64
	v_cvt_pk_bf16_f32 v88, v88, v89
	v_cvt_pk_bf16_f32 v89, v84, v85
	v_add_f32_dpp v64, v64, v64 quad_perm:[1,0,3,2] row_mask:0xf bank_mask:0xf bound_ctrl:1
	global_store_dwordx2 v[82:83], v[88:89], off
	s_nop 0
	v_add_f32_dpp v64, v64, v64 quad_perm:[2,3,0,1] row_mask:0xf bank_mask:0xf bound_ctrl:1
	s_nop 1
	v_add_f32_dpp v64, v64, v64 row_half_mirror row_mask:0xf bank_mask:0xf bound_ctrl:1
	s_nop 1
	v_mov_b32_dpp v65, v64 row_mirror row_mask:0xf bank_mask:0xf bound_ctrl:1
	s_and_saveexec_b64 s[4:5], s[36:37]
	s_cbranch_execz .LBB0_709
	v_ashrrev_i32_e32 v97, 31, v96
	v_lshl_add_u64 v[66:67], s[52:53], 0, v[68:69]
	v_lshl_add_u64 v[82:83], v[96:97], 0, v[128:129]
	v_lshl_add_u64 v[66:67], v[82:83], 2, v[66:67]
	v_add_f32_e32 v64, v64, v65
	global_store_dword v[66:67], v64, off offset:96

.LBB0_710:
	v_or_b32_e32 v82, 28, v128
	v_or_b32_e32 v84, v96, v82
	v_ashrrev_i32_e32 v85, 31, v84
	v_lshlrev_b64 v[64:65], 12, v[84:85]
	v_lshl_add_u64 v[64:65], s[40:41], 0, v[64:65]
	v_lshl_add_u64 v[100:101], v[98:99], 2, v[64:65]
	s_movk_i32 s4, 0x1000
	v_cmp_gt_i32_e32 vcc, s4, v84
	s_nop 1
	v_cndmask_b32_e32 v71, v71, v102, vcc
	v_and_b32_e32 v71, 1, v71
	v_cmp_eq_u32_e32 vcc, 1, v71
	s_nop 1
	v_cndmask_b32_e64 v71, v171, 0, vcc
	v_add_u32_e32 v71, v103, v71
	ds_read_b128 v[88:91], v86 offset:7616
	ds_read_b128 v[92:95], v71
	s_and_b64 vcc, exec, s[0:1]
	s_waitcnt lgkmcnt(0)
	v_pk_fma_f32 v[66:67], v[90:91], v[94:95], v[228:229]
	v_pk_fma_f32 v[64:65], v[88:89], v[92:93], v[226:227]
	global_store_dwordx4 v[100:101], v[64:67], off
	s_cbranch_vccnz .LBB0_714
	ds_read_b128 v[88:91], v71 offset:2048
	v_lshlrev_b64 v[84:85], 10, v[84:85]
	v_lshl_add_u64 v[84:85], v[84:85], 1, s[42:43]
	v_lshl_add_u64 v[84:85], v[98:99], 1, v[84:85]
	s_waitcnt lgkmcnt(0)
	v_pk_mul_f32 v[88:89], v[64:65], v[88:89]
	v_pk_mul_f32 v[64:65], v[64:65], v[64:65]
	v_pk_mul_f32 v[90:91], v[66:67], v[90:91]
	v_pk_mul_f32 v[66:67], v[66:67], v[66:67]
	v_add_f32_e32 v64, v64, v65
	v_add_f32_e32 v64, v66, v64
	v_add_f32_e32 v64, v67, v64
	v_cvt_pk_bf16_f32 v88, v88, v89
	v_cvt_pk_bf16_f32 v89, v90, v91
	v_add_f32_dpp v64, v64, v64 quad_perm:[1,0,3,2] row_mask:0xf bank_mask:0xf bound_ctrl:1
	global_store_dwordx2 v[84:85], v[88:89], off
	s_nop 0
	v_add_f32_dpp v64, v64, v64 quad_perm:[2,3,0,1] row_mask:0xf bank_mask:0xf bound_ctrl:1
	s_nop 1
	v_add_f32_dpp v64, v64, v64 row_half_mirror row_mask:0xf bank_mask:0xf bound_ctrl:1
	s_nop 1
	v_mov_b32_dpp v65, v64 row_mirror row_mask:0xf bank_mask:0xf bound_ctrl:1
	s_and_saveexec_b64 s[4:5], s[36:37]
	s_cbranch_execz .LBB0_713
	v_ashrrev_i32_e32 v97, 31, v96
	v_lshl_add_u64 v[66:67], s[52:53], 0, v[68:69]
	v_lshl_add_u64 v[84:85], v[96:97], 0, v[128:129]
	v_lshl_add_u64 v[66:67], v[84:85], 2, v[66:67]
	v_add_f32_e32 v64, v64, v65
	global_store_dword v[66:67], v64, off offset:112

.LBB0_1222:
	s_waitcnt vmcnt(0)
	ds_write_b32 v2, v246
	v_ashrrev_i32_e32 v103, 6, v100
	v_lshrrev_b32_e32 v0, 30, v103
	v_add_u32_e32 v0, v103, v0
	v_ashrrev_i32_e32 v10, 2, v0
	v_mul_i32_i24_e32 v0, 4, v10
	v_ashrrev_i32_e32 v6, 3, v100
	v_sub_u32_e32 v11, v103, v0
	v_lshrrev_b32_e32 v13, 4, v100
	v_add_u32_e32 v0, s4, v6
	v_xor_b32_e32 v7, v13, v100
	v_ashrrev_i32_e32 v1, 31, v0
	v_lshlrev_b64 v[0:1], 11, v[0:1]
	v_lshlrev_b32_e32 v7, 4, v7
	v_lshlrev_b32_e32 v109, 4, v100
	s_and_b32 s8, s2, 0xffffff00
	v_lshl_add_u64 v[4:5], s[46:47], 0, v[0:1]
	v_and_b32_e32 v128, 0x70, v7
	v_readfirstlane_b32 s2, v109
	v_add_u32_e32 v14, 0x2000, v109
	v_lshl_add_u64 v[4:5], v[4:5], 0, v[128:129]
	s_mov_b32 m0, s2
	s_mov_b64 s[10:11], 0x20000
	v_readfirstlane_b32 s2, v14
	ds_write_b32 v2, v3 offset:2048
	v_lshl_add_u64 v[2:3], v[4:5], 0, s[10:11]
	s_mov_b32 m0, s2
	s_mov_b64 s[12:13], 0x40000
	v_lshl_add_u64 v[2:3], v[4:5], 0, s[12:13]
	v_add_u32_e32 v4, 0x4000, v109
	v_add_u32_e32 v6, s8, v6
	v_readfirstlane_b32 s2, v4
	v_ashrrev_i32_e32 v7, 31, v6
	s_mov_b32 m0, s2
	v_lshlrev_b64 v[6:7], 11, v[6:7]
	v_add_u32_e32 v2, 0x6000, v109
	v_lshl_add_u64 v[8:9], s[56:57], 0, v[6:7]
	v_readfirstlane_b32 s2, v2
	v_add_u32_e32 v4, 0x8000, v109
	v_lshl_add_u64 v[8:9], v[8:9], 0, v[128:129]
	s_mov_b32 m0, s2
	v_readfirstlane_b32 s2, v4
	v_add_u32_e32 v4, 0xa000, v109
	v_lshl_add_u64 v[2:3], v[8:9], 0, s[10:11]
	s_mov_b32 m0, s2
	v_readfirstlane_b32 s2, v4
	v_lshl_add_u64 v[2:3], v[8:9], 0, s[12:13]
	s_mov_b32 m0, s2
	s_mov_b64 s[2:3], 0x60000
	v_add_u32_e32 v4, 0xc000, v109
	v_lshl_add_u64 v[2:3], v[8:9], 0, s[2:3]
	v_readfirstlane_b32 s2, v4
	s_mov_b32 m0, s2
	v_and_b32_e32 v102, 31, v100
	v_lshlrev_b32_e32 v105, 6, v11
	v_or_b32_e32 v3, v105, v102
	v_mul_i32_i24_e32 v106, 0x60, v10
	v_bfe_u32 v12, v100, 5, 1
	v_lshrrev_b32_e32 v104, 1, v100
	v_lshlrev_b32_e32 v112, 7, v3
	v_or_b32_e32 v3, v106, v102
	v_bfe_u32 v2, v100, 1, 3
	v_lshlrev_b32_e32 v113, 7, v3
	v_bitop3_b32 v3, v12, v104, 7 bitop3:0x78
	v_lshlrev_b32_e32 v111, 4, v3
	v_bitop3_b32 v3, v12, v2, 2 bitop3:0x36
	v_lshlrev_b32_e32 v110, 4, v3
	v_bitop3_b32 v3, v12, v2, 4 bitop3:0x36
	v_bitop3_b32 v2, v12, v2, 6 bitop3:0x36
	v_lshlrev_b32_e32 v107, 4, v2
	v_bitop3_b32 v2, v13, 7, v100 bitop3:0x48
	v_lshlrev_b32_e32 v2, 4, v2
	v_or_b32_e32 v6, v6, v2
	v_or_b32_e32 v0, v0, v2
	v_and_b32_e32 v101, 63, v100
	v_lshlrev_b32_e32 v108, 4, v3
	v_add_u32_e32 v114, 0x6000, v112
	v_lshl_add_u64 v[96:97], s[58:59], 0, v[6:7]
	v_lshl_add_u64 v[98:99], s[14:15], 0, v[0:1]
	s_mov_b32 s7, 0
	s_mov_b64 s[2:3], 0
	v_mov_b32_e32 v33, v32
	v_mov_b32_e32 v34, v32
	v_mov_b32_e32 v35, v32
	v_mov_b32_e32 v36, v32
	v_mov_b32_e32 v37, v32
	v_mov_b32_e32 v38, v32
	v_mov_b32_e32 v39, v32
	v_mov_b32_e32 v40, v32
	v_mov_b32_e32 v41, v32
	v_mov_b32_e32 v42, v32
	v_mov_b32_e32 v43, v32
	v_mov_b32_e32 v44, v32
	v_mov_b32_e32 v45, v32
	v_mov_b32_e32 v46, v32
	v_mov_b32_e32 v47, v32
	v_mov_b32_e32 v64, v32
	v_mov_b32_e32 v65, v32
	v_mov_b32_e32 v66, v32
	v_mov_b32_e32 v67, v32
	v_mov_b32_e32 v68, v32
	v_mov_b32_e32 v69, v32
	v_mov_b32_e32 v70, v32
	v_mov_b32_e32 v71, v32
	v_mov_b32_e32 v72, v32
	v_mov_b32_e32 v73, v32
	v_mov_b32_e32 v74, v32
	v_mov_b32_e32 v75, v32
	v_mov_b32_e32 v76, v32
	v_mov_b32_e32 v77, v32
	v_mov_b32_e32 v78, v32
	v_mov_b32_e32 v79, v32
	v_mov_b32_e32 v0, v32
	v_mov_b32_e32 v1, v32
	v_mov_b32_e32 v2, v32
	v_mov_b32_e32 v3, v32
	v_mov_b32_e32 v4, v32
	v_mov_b32_e32 v5, v32
	v_mov_b32_e32 v6, v32
	v_mov_b32_e32 v7, v32
	v_mov_b32_e32 v8, v32
	v_mov_b32_e32 v9, v32
	v_mov_b32_e32 v10, v32
	v_mov_b32_e32 v11, v32
	v_mov_b32_e32 v12, v32
	v_mov_b32_e32 v13, v32
	v_mov_b32_e32 v14, v32
	v_mov_b32_e32 v15, v32
	v_mov_b32_e32 v80, v32
	v_mov_b32_e32 v81, v32
	v_mov_b32_e32 v82, v32
	v_mov_b32_e32 v83, v32
	v_mov_b32_e32 v84, v32
	v_mov_b32_e32 v85, v32
	v_mov_b32_e32 v86, v32
	v_mov_b32_e32 v87, v32
	v_mov_b32_e32 v88, v32
	v_mov_b32_e32 v89, v32
	v_mov_b32_e32 v90, v32
	v_mov_b32_e32 v91, v32
	v_mov_b32_e32 v92, v32
	v_mov_b32_e32 v93, v32
	v_mov_b32_e32 v94, v32
	v_mov_b32_e32 v95, v32
	v_mov_b32_e32 v48, v32
	v_mov_b32_e32 v49, v32
	v_mov_b32_e32 v50, v32
	v_mov_b32_e32 v51, v32
	v_mov_b32_e32 v52, v32
	v_mov_b32_e32 v53, v32
	v_mov_b32_e32 v54, v32
	v_mov_b32_e32 v55, v32
	v_mov_b32_e32 v56, v32
	v_mov_b32_e32 v57, v32
	v_mov_b32_e32 v58, v32
	v_mov_b32_e32 v59, v32
	v_mov_b32_e32 v60, v32
	v_mov_b32_e32 v61, v32
	v_mov_b32_e32 v62, v32
	v_mov_b32_e32 v63, v32
	v_mov_b32_e32 v16, v32
	v_mov_b32_e32 v17, v32
	v_mov_b32_e32 v18, v32
	v_mov_b32_e32 v19, v32
	v_mov_b32_e32 v20, v32
	v_mov_b32_e32 v21, v32
	v_mov_b32_e32 v22, v32
	v_mov_b32_e32 v23, v32
	v_mov_b32_e32 v24, v32
	v_mov_b32_e32 v25, v32
	v_mov_b32_e32 v26, v32
	v_mov_b32_e32 v27, v32
	v_mov_b32_e32 v28, v32
	v_mov_b32_e32 v29, v32
	v_mov_b32_e32 v30, v32
	v_mov_b32_e32 v31, v32
	s_mov_b64 s[12:13], 0x8794080
	s_mov_b64 s[16:17], 0x87b4080
	s_mov_b64 s[18:19], 0x87d4080
	v_add_u32_e32 v243, s4, v106
	v_lshrrev_b32_e32 v244, 4, v101
	v_or_b32_e32 v243, v243, v244
	v_and_b32_e32 v244, 15, v100
	v_add_u32_e32 v245, s8, v105
	v_lshl_or_b32 v244, v244, 2, v245
	v_lshlrev_b32_e32 v243, 12, v243
	v_lshl_add_u32 v243, v244, 2, v243
	global_load_dwordx4 v[198:201], v243, s[42:43]
	v_add_u32_e32 v243, 0x4000, v243
	global_load_dwordx4 v[202:205], v243, s[42:43]
	v_add_u32_e32 v243, 0x4000, v243
	global_load_dwordx4 v[206:209], v243, s[42:43]
	v_add_u32_e32 v243, 0x4000, v243
	global_load_dwordx4 v[210:213], v243, s[42:43]
	v_add_u32_e32 v243, 0x4000, v243
	global_load_dwordx4 v[214:217], v243, s[42:43]
	v_add_u32_e32 v243, 0x4000, v243
	global_load_dwordx4 v[218:221], v243, s[42:43]
	v_add_u32_e32 v243, 0x4000, v243
	global_load_dwordx4 v[222:225], v243, s[42:43]
	v_add_u32_e32 v243, 0x4000, v243
	global_load_dwordx4 v[226:229], v243, s[42:43]
.LBB0_1223:
	s_add_i32 s9, s7, 1
	s_bitcmp1_b32 s9, 0
	s_cselect_b32 s10, 0xe000, 0
	v_add_u32_e32 v115, s10, v109
	v_lshl_add_u64 v[116:117], v[98:99], 0, s[2:3]
	v_readfirstlane_b32 s10, v115
	v_add_u32_e32 v120, 0x2000, v115
	v_lshl_add_u64 v[118:119], v[116:117], 0, s[12:13]
	s_mov_b32 m0, s10
	v_readfirstlane_b32 s10, v120
	s_waitcnt vmcnt(0)
	s_waitcnt vmcnt(0) lgkmcnt(0)
	s_barrier
	global_load_lds_dwordx4 v[118:119], off
	v_lshl_add_u64 v[118:119], v[116:117], 0, s[16:17]
	s_mov_b32 m0, s10
	v_lshl_add_u64 v[116:117], v[116:117], 0, s[18:19]
	global_load_lds_dwordx4 v[118:119], off
	v_add_u32_e32 v118, 0x4000, v115
	v_add_u32_e32 v120, 0x6000, v115
	v_readfirstlane_b32 s10, v118
	s_mov_b32 m0, s10
	s_mov_b64 s[10:11], 0x5f14080
	global_load_lds_dwordx4 v[116:117], off
	v_lshl_add_u64 v[116:117], v[96:97], 0, s[2:3]
	v_lshl_add_u64 v[118:119], v[116:117], 0, s[10:11]
	v_readfirstlane_b32 s10, v120
	s_mov_b32 m0, s10
	s_mov_b64 s[10:11], 0x5f34080
	v_add_u32_e32 v120, 0x8000, v115
	global_load_lds_dwordx4 v[118:119], off
	v_lshl_add_u64 v[118:119], v[116:117], 0, s[10:11]
	v_readfirstlane_b32 s10, v120
	s_mov_b32 m0, s10
	s_mov_b64 s[10:11], 0x5f54080
	v_add_u32_e32 v120, 0xa000, v115
	global_load_lds_dwordx4 v[118:119], off
	v_lshl_add_u64 v[118:119], v[116:117], 0, s[10:11]
	v_readfirstlane_b32 s10, v120
	s_mov_b32 m0, s10
	s_mov_b64 s[10:11], 0x5f74080
	v_add_u32_e32 v115, 0xc000, v115
	v_lshl_add_u64 v[116:117], v[116:117], 0, s[10:11]
	v_readfirstlane_b32 s10, v115
	global_load_lds_dwordx4 v[118:119], off
	s_mov_b32 m0, s10
	s_nop 0
	global_load_lds_dwordx4 v[116:117], off
	s_bitcmp1_b32 s7, 0
	s_cselect_b32 s7, 0xe000, 0
	v_add_u32_e32 v115, s7, v114
	v_add_u32_e32 v120, v115, v111
	ds_read_b128 v[116:119], v120 offset:0
	v_add_u32_e32 v128, s7, v113
	ds_read_b128 v[120:123], v120 offset:0x1000
	v_add_u32_e32 v134, v128, v111
	ds_read_b128 v[124:127], v134 offset:0
	ds_read_b128 v[130:133], v134 offset:0x1000
	ds_read_b128 v[134:137], v134 offset:0x2000
	v_add_u32_e32 v148, v115, v110
	ds_read_b128 v[144:147], v148 offset:0
	ds_read_b128 v[148:151], v148 offset:0x1000
	v_add_u32_e32 v152, v128, v110
	ds_read_b128 v[182:185], v152 offset:0
	ds_read_b128 v[186:189], v152 offset:0x1000
	ds_read_b128 v[190:193], v152 offset:0x2000
	s_waitcnt lgkmcnt(5)
	s_nop 0
	v_mfma_f32_32x32x16_bf16 v[64:79], v[116:119], v[124:127], v[64:79]
	v_mfma_f32_32x32x16_bf16 v[32:47], v[116:119], v[130:133], v[32:47]
	v_mfma_f32_32x32x16_bf16 v[0:15], v[116:119], v[134:137], v[0:15]
	v_mfma_f32_32x32x16_bf16 v[80:95], v[120:123], v[124:127], v[80:95]
	v_mfma_f32_32x32x16_bf16 v[48:63], v[120:123], v[130:133], v[48:63]
	v_mfma_f32_32x32x16_bf16 v[16:31], v[120:123], v[134:137], v[16:31]
	v_add_u32_e32 v120, v115, v108
	ds_read_b128 v[116:119], v120 offset:0
	ds_read_b128 v[120:123], v120 offset:0x1000
	v_add_u32_e32 v134, v128, v108
	ds_read_b128 v[124:127], v134 offset:0
	ds_read_b128 v[130:133], v134 offset:0x1000
	ds_read_b128 v[134:137], v134 offset:0x2000
	s_waitcnt lgkmcnt(5)
	s_nop 0
	v_mfma_f32_32x32x16_bf16 v[64:79], v[144:147], v[182:185], v[64:79]
	v_mfma_f32_32x32x16_bf16 v[32:47], v[144:147], v[186:189], v[32:47]
	v_mfma_f32_32x32x16_bf16 v[0:15], v[144:147], v[190:193], v[0:15]
	v_mfma_f32_32x32x16_bf16 v[80:95], v[148:151], v[182:185], v[80:95]
	v_mfma_f32_32x32x16_bf16 v[48:63], v[148:151], v[186:189], v[48:63]
	v_mfma_f32_32x32x16_bf16 v[16:31], v[148:151], v[190:193], v[16:31]
	v_add_u32_e32 v115, v115, v107
	ds_read_b128 v[144:147], v115 offset:0
	ds_read_b128 v[148:151], v115 offset:0x1000
	v_add_u32_e32 v115, v128, v107
	ds_read_b128 v[182:185], v115 offset:0
	ds_read_b128 v[186:189], v115 offset:0x1000
	ds_read_b128 v[190:193], v115 offset:0x2000
	s_waitcnt lgkmcnt(5)
	s_nop 0
	v_mfma_f32_32x32x16_bf16 v[64:79], v[116:119], v[124:127], v[64:79]
	v_mfma_f32_32x32x16_bf16 v[32:47], v[116:119], v[130:133], v[32:47]
	v_mfma_f32_32x32x16_bf16 v[0:15], v[116:119], v[134:137], v[0:15]
	v_mfma_f32_32x32x16_bf16 v[80:95], v[120:123], v[124:127], v[80:95]
	v_mfma_f32_32x32x16_bf16 v[48:63], v[120:123], v[130:133], v[48:63]
	v_mfma_f32_32x32x16_bf16 v[16:31], v[120:123], v[134:137], v[16:31]
	s_waitcnt lgkmcnt(0)
	s_nop 0
	v_mfma_f32_32x32x16_bf16 v[64:79], v[144:147], v[182:185], v[64:79]
	v_mfma_f32_32x32x16_bf16 v[32:47], v[144:147], v[186:189], v[32:47]
	v_mfma_f32_32x32x16_bf16 v[0:15], v[144:147], v[190:193], v[0:15]
	v_mfma_f32_32x32x16_bf16 v[80:95], v[148:151], v[182:185], v[80:95]
	v_mfma_f32_32x32x16_bf16 v[48:63], v[148:151], v[186:189], v[48:63]
	v_mfma_f32_32x32x16_bf16 v[16:31], v[148:151], v[190:193], v[16:31]
	s_add_u32 s2, s2, 0x80
	s_addc_u32 s3, s3, 0
	s_cmpk_eq_i32 s2, 0x780
	s_mov_b32 s7, s9
	s_cbranch_scc0 .LBB0_1223
	s_waitcnt vmcnt(0)
	s_waitcnt vmcnt(0) lgkmcnt(0)
	s_barrier
	v_add_u32_e32 v109, 0x14000, v112
	v_add_u32_e32 v112, v109, v111
	ds_read_b128 v[96:99], v112 offset:0
	v_add_u32_e32 v128, 0xe000, v113
	ds_read_b128 v[112:115], v112 offset:0x1000
	v_add_u32_e32 v111, v128, v111
	ds_read_b128 v[116:119], v111 offset:0
	ds_read_b128 v[120:123], v111 offset:0x1000
	ds_read_b128 v[124:127], v111 offset:0x2000
	v_add_u32_e32 v111, v109, v110
	ds_read_b128 v[130:133], v111 offset:0
	ds_read_b128 v[134:137], v111 offset:0x1000
	v_add_u32_e32 v110, v128, v110
	ds_read_b128 v[144:147], v110 offset:0
	ds_read_b128 v[148:151], v110 offset:0x1000
	ds_read_b128 v[182:185], v110 offset:0x2000
	s_waitcnt lgkmcnt(5)
	s_nop 0
	v_mfma_f32_32x32x16_bf16 v[64:79], v[96:99], v[116:119], v[64:79]
	v_mfma_f32_32x32x16_bf16 v[32:47], v[96:99], v[120:123], v[32:47]
	v_mfma_f32_32x32x16_bf16 v[0:15], v[96:99], v[124:127], v[0:15]
	v_mfma_f32_32x32x16_bf16 v[48:63], v[112:115], v[120:123], v[48:63]
	v_mfma_f32_32x32x16_bf16 v[16:31], v[112:115], v[124:127], v[16:31]
	v_mfma_f32_32x32x16_bf16 v[80:95], v[112:115], v[116:119], v[80:95]
	v_add_u32_e32 v110, v109, v108
	ds_read_b128 v[96:99], v110 offset:0
	ds_read_b128 v[110:113], v110 offset:0x1000
	v_add_u32_e32 v108, v128, v108
	ds_read_b128 v[114:117], v108 offset:0
	ds_read_b128 v[118:121], v108 offset:0x1000
	ds_read_b128 v[122:125], v108 offset:0x2000
	s_waitcnt lgkmcnt(5)
	s_nop 0
	v_mfma_f32_32x32x16_bf16 v[64:79], v[130:133], v[144:147], v[64:79]
	v_mfma_f32_32x32x16_bf16 v[32:47], v[130:133], v[148:151], v[32:47]
	v_mfma_f32_32x32x16_bf16 v[0:15], v[130:133], v[182:185], v[0:15]
	v_mfma_f32_32x32x16_bf16 v[48:63], v[134:137], v[148:151], v[48:63]
	v_mfma_f32_32x32x16_bf16 v[16:31], v[134:137], v[182:185], v[16:31]
	v_mfma_f32_32x32x16_bf16 v[80:95], v[134:137], v[144:147], v[80:95]
	v_add_u32_e32 v108, v109, v107
	ds_read_b128 v[130:133], v108 offset:0
	ds_read_b128 v[134:137], v108 offset:0x1000
	v_add_u32_e32 v107, v128, v107
	ds_read_b128 v[144:147], v107 offset:0
	ds_read_b128 v[148:151], v107 offset:0x1000
	ds_read_b128 v[182:185], v107 offset:0x2000
	s_waitcnt lgkmcnt(5)
	s_nop 0
	v_mfma_f32_32x32x16_bf16 v[64:79], v[96:99], v[114:117], v[64:79]
	v_mfma_f32_32x32x16_bf16 v[32:47], v[96:99], v[118:121], v[32:47]
	v_mfma_f32_32x32x16_bf16 v[0:15], v[96:99], v[122:125], v[0:15]
	v_mfma_f32_32x32x16_bf16 v[48:63], v[110:113], v[118:121], v[48:63]
	v_mfma_f32_32x32x16_bf16 v[16:31], v[110:113], v[122:125], v[16:31]
	v_mfma_f32_32x32x16_bf16 v[80:95], v[110:113], v[114:117], v[80:95]
	s_waitcnt lgkmcnt(0)
	s_nop 0
	v_mfma_f32_32x32x16_bf16 v[64:79], v[130:133], v[144:147], v[64:79]
	v_mfma_f32_32x32x16_bf16 v[32:47], v[130:133], v[148:151], v[32:47]
	v_mfma_f32_32x32x16_bf16 v[0:15], v[130:133], v[182:185], v[0:15]
	v_mfma_f32_32x32x16_bf16 v[48:63], v[134:137], v[148:151], v[48:63]
	v_mfma_f32_32x32x16_bf16 v[16:31], v[134:137], v[182:185], v[16:31]
	v_mfma_f32_32x32x16_bf16 v[80:95], v[134:137], v[144:147], v[80:95]
	v_add_u32_e32 v96, s4, v106
	v_lshrrev_b32_e32 v128, 4, v101
	v_and_b32_e32 v112, 15, v100
	v_or_b32_e32 v100, v96, v128
	v_add_u32_e32 v105, s8, v105
	v_ashrrev_i32_e32 v101, 31, v100
	v_lshl_or_b32 v98, v112, 2, v105
	v_lshlrev_b64 v[106:107], 12, v[100:101]
	v_ashrrev_i32_e32 v99, 31, v98
	v_lshl_add_u64 v[106:107], s[42:43], 0, v[106:107]
	v_lshl_add_u64 v[110:111], v[98:99], 2, v[106:107]
	s_barrier
	v_add_co_u32_e32 v182, vcc, 0x20000, v110
	s_nop 1
	v_addc_co_u32_e32 v183, vcc, 0, v111, vcc
	global_load_dwordx4 v[184:187], v[182:183], off
	v_add_co_u32_e32 v182, vcc, 0x4000, v182
	s_nop 1
	v_addc_co_u32_e32 v183, vcc, 0, v183, vcc
	global_load_dwordx4 v[188:191], v[182:183], off
	v_add_co_u32_e32 v182, vcc, 0x4000, v182
	s_nop 1
	v_addc_co_u32_e32 v183, vcc, 0, v183, vcc
	global_load_dwordx4 v[192:195], v[182:183], off
	v_add_co_u32_e32 v182, vcc, 0x4000, v182
	s_nop 1
	v_addc_co_u32_e32 v183, vcc, 0, v183, vcc
	global_load_dwordx4 v[116:119], v[182:183], off
	v_add_co_u32_e32 v182, vcc, 0x4000, v182
	s_nop 1
	v_addc_co_u32_e32 v183, vcc, 0, v183, vcc
	global_load_dwordx4 v[120:123], v[182:183], off
	v_add_co_u32_e32 v182, vcc, 0x4000, v182
	s_nop 1
	v_addc_co_u32_e32 v183, vcc, 0, v183, vcc
	global_load_dwordx4 v[124:127], v[182:183], off
	v_add_co_u32_e32 v182, vcc, 0x4000, v182
	s_nop 1
	v_addc_co_u32_e32 v183, vcc, 0, v183, vcc
	global_load_dwordx4 v[130:133], v[182:183], off
	v_add_co_u32_e32 v182, vcc, 0x4000, v182
	s_nop 1
	v_addc_co_u32_e32 v183, vcc, 0, v183, vcc
	global_load_dwordx4 v[134:137], v[182:183], off
	s_movk_i32 s2, 0x2400
	s_cmp_lt_i32 s5, 22
	v_mul_lo_u32 v97, v103, s2
	s_cselect_b64 s[2:3], -1, 0
	s_cmp_gt_i32 s5, 21
	s_movk_i32 s5, 0x110
	v_and_b32_e32 v103, 16, v104
	v_mad_u32_u24 v104, v102, s5, v97
	v_add_u32_e32 v113, 0xfffff000, v96
	v_cndmask_b32_e64 v102, 0, 1, s[2:3]
	s_cselect_b64 s[2:3], -1, 0
	s_add_i32 s7, s4, 0xfffff000
	v_add_u32_e32 v104, v104, v103
	ds_write_b128 v104, v[64:67]
	ds_write_b128 v104, v[68:71] offset:32
	ds_write_b128 v104, v[72:75] offset:64
	ds_write_b128 v104, v[76:79] offset:96
	ds_write_b128 v104, v[80:83] offset:128
	ds_write_b128 v104, v[84:87] offset:160
	ds_write_b128 v104, v[88:91] offset:192
	ds_write_b128 v104, v[92:95] offset:224
	v_xor_b32_e32 v64, s7, v113
	s_movk_i32 s4, 0x400
	v_lshl_or_b32 v97, v112, 4, v97
	v_cmp_gt_u32_e32 vcc, s4, v64
	v_mad_u32_u24 v115, v128, s5, v97
	s_and_b64 s[4:5], s[2:3], vcc
	v_cndmask_b32_e64 v71, 0, 1, s[4:5]
	s_movk_i32 s4, 0x1000
	v_cmp_gt_i32_e32 vcc, s4, v100
	v_subrev_u32_e32 v114, s8, v98
	v_lshl_add_u32 v103, v114, 2, v167
	v_cndmask_b32_e32 v64, v71, v102, vcc
	v_and_b32_e32 v64, 1, v64
	v_cmp_eq_u32_e32 vcc, 1, v64
	v_ashrrev_i32_e32 v68, 6, v105
	s_mov_b32 s4, 0xc000
	v_cndmask_b32_e64 v64, v171, 0, vcc
	v_add_u32_e32 v70, v103, v64
	ds_read_b128 v[64:67], v115
	ds_read_b128 v[72:75], v70
	v_cmp_eq_u32_e64 s[40:41], 0, v112
	v_mad_i64_i32 v[68:69], s[4:5], v68, s4, 0
	s_and_b64 vcc, exec, s[0:1]
	s_waitcnt lgkmcnt(0)
	v_pk_fma_f32 v[66:67], v[66:67], v[74:75], v[200:201]
	v_pk_fma_f32 v[64:65], v[64:65], v[72:73], v[198:199]
	global_store_dwordx4 v[110:111], v[64:67], off
	s_cbranch_vccnz .LBB0_1228
	ds_read_b128 v[72:75], v70 offset:2048
	v_lshlrev_b64 v[76:77], 10, v[100:101]
	v_lshl_add_u64 v[76:77], v[76:77], 1, s[44:45]
	v_lshl_add_u64 v[76:77], v[98:99], 1, v[76:77]
	s_waitcnt lgkmcnt(0)
	v_pk_mul_f32 v[72:73], v[64:65], v[72:73]
	v_pk_mul_f32 v[64:65], v[64:65], v[64:65]
	v_pk_mul_f32 v[74:75], v[66:67], v[74:75]
	v_pk_mul_f32 v[66:67], v[66:67], v[66:67]
	v_add_f32_e32 v64, v64, v65
	v_add_f32_e32 v64, v66, v64
	v_add_f32_e32 v64, v67, v64
	v_cvt_pk_bf16_f32 v72, v72, v73
	v_cvt_pk_bf16_f32 v73, v74, v75
	v_add_f32_dpp v64, v64, v64 quad_perm:[1,0,3,2] row_mask:0xf bank_mask:0xf bound_ctrl:1
	global_store_dwordx2 v[76:77], v[72:73], off
	s_nop 0
	v_add_f32_dpp v64, v64, v64 quad_perm:[2,3,0,1] row_mask:0xf bank_mask:0xf bound_ctrl:1
	s_nop 1
	v_add_f32_dpp v64, v64, v64 row_half_mirror row_mask:0xf bank_mask:0xf bound_ctrl:1
	s_nop 1
	v_mov_b32_dpp v65, v64 row_mirror row_mask:0xf bank_mask:0xf bound_ctrl:1
	s_and_saveexec_b64 s[4:5], s[40:41]
	s_cbranch_execz .LBB0_1227
	v_lshl_add_u64 v[66:67], s[48:49], 0, v[68:69]
	v_lshl_add_u64 v[66:67], v[100:101], 2, v[66:67]
	v_add_f32_e32 v64, v64, v65
	global_store_dword v[66:67], v64, off

.LBB0_1228:
	v_or_b32_e32 v70, 4, v128
	v_or_b32_e32 v72, v96, v70
	v_ashrrev_i32_e32 v73, 31, v72
	v_lshlrev_b64 v[64:65], 12, v[72:73]
	v_lshl_add_u64 v[64:65], s[42:43], 0, v[64:65]
	v_lshl_add_u64 v[84:85], v[98:99], 2, v[64:65]
	s_movk_i32 s4, 0x1000
	v_mul_u32_u24_e32 v74, 0x110, v128
	v_cmp_gt_i32_e32 vcc, s4, v72
	v_add_u32_e32 v86, v74, v97
	s_nop 0
	v_cndmask_b32_e32 v74, v71, v102, vcc
	v_and_b32_e32 v74, 1, v74
	v_cmp_eq_u32_e32 vcc, 1, v74
	s_nop 1
	v_cndmask_b32_e64 v74, v171, 0, vcc
	v_add_u32_e32 v74, v103, v74
	ds_read_b128 v[76:79], v86 offset:1088
	ds_read_b128 v[80:83], v74
	s_and_b64 vcc, exec, s[0:1]
	s_waitcnt lgkmcnt(0)
	v_pk_fma_f32 v[66:67], v[78:79], v[82:83], v[204:205]
	v_pk_fma_f32 v[64:65], v[76:77], v[80:81], v[202:203]
	global_store_dwordx4 v[84:85], v[64:67], off
	s_cbranch_vccnz .LBB0_1232
	ds_read_b128 v[74:77], v74 offset:2048
	v_lshlrev_b64 v[72:73], 10, v[72:73]
	v_lshl_add_u64 v[72:73], v[72:73], 1, s[44:45]
	v_lshl_add_u64 v[72:73], v[98:99], 1, v[72:73]
	s_waitcnt lgkmcnt(0)
	v_pk_mul_f32 v[74:75], v[64:65], v[74:75]
	v_pk_mul_f32 v[64:65], v[64:65], v[64:65]
	v_pk_mul_f32 v[76:77], v[66:67], v[76:77]
	v_pk_mul_f32 v[66:67], v[66:67], v[66:67]
	v_add_f32_e32 v64, v64, v65
	v_add_f32_e32 v64, v66, v64
	v_add_f32_e32 v64, v67, v64
	v_cvt_pk_bf16_f32 v74, v74, v75
	v_cvt_pk_bf16_f32 v75, v76, v77
	v_add_f32_dpp v64, v64, v64 quad_perm:[1,0,3,2] row_mask:0xf bank_mask:0xf bound_ctrl:1
	global_store_dwordx2 v[72:73], v[74:75], off
	s_nop 0
	v_add_f32_dpp v64, v64, v64 quad_perm:[2,3,0,1] row_mask:0xf bank_mask:0xf bound_ctrl:1
	s_nop 1
	v_add_f32_dpp v64, v64, v64 row_half_mirror row_mask:0xf bank_mask:0xf bound_ctrl:1
	s_nop 1
	v_mov_b32_dpp v65, v64 row_mirror row_mask:0xf bank_mask:0xf bound_ctrl:1
	s_and_saveexec_b64 s[4:5], s[40:41]
	s_cbranch_execz .LBB0_1231
	v_ashrrev_i32_e32 v97, 31, v96
	v_lshl_add_u64 v[66:67], s[48:49], 0, v[68:69]
	v_lshl_add_u64 v[72:73], v[96:97], 0, v[128:129]
	v_lshl_add_u64 v[66:67], v[72:73], 2, v[66:67]
	v_add_f32_e32 v64, v64, v65
	global_store_dword v[66:67], v64, off offset:16

.LBB0_1232:
	v_or_b32_e32 v72, 8, v128
	v_or_b32_e32 v74, v96, v72
	v_ashrrev_i32_e32 v75, 31, v74
	v_lshlrev_b64 v[64:65], 12, v[74:75]
	v_lshl_add_u64 v[64:65], s[42:43], 0, v[64:65]
	v_lshl_add_u64 v[84:85], v[98:99], 2, v[64:65]
	s_movk_i32 s4, 0x1000
	v_cmp_gt_i32_e32 vcc, s4, v74
	s_nop 1
	v_cndmask_b32_e32 v73, v71, v102, vcc
	v_and_b32_e32 v73, 1, v73
	v_cmp_eq_u32_e32 vcc, 1, v73
	s_nop 1
	v_cndmask_b32_e64 v73, v171, 0, vcc
	v_add_u32_e32 v73, v103, v73
	ds_read_b128 v[76:79], v86 offset:2176
	ds_read_b128 v[80:83], v73
	s_and_b64 vcc, exec, s[0:1]
	s_waitcnt lgkmcnt(0)
	v_pk_fma_f32 v[66:67], v[78:79], v[82:83], v[208:209]
	v_pk_fma_f32 v[64:65], v[76:77], v[80:81], v[206:207]
	global_store_dwordx4 v[84:85], v[64:67], off
	s_cbranch_vccnz .LBB0_1236
	ds_read_b128 v[76:79], v73 offset:2048
	v_lshlrev_b64 v[74:75], 10, v[74:75]
	v_lshl_add_u64 v[74:75], v[74:75], 1, s[44:45]
	v_lshl_add_u64 v[74:75], v[98:99], 1, v[74:75]
	s_waitcnt lgkmcnt(0)
	v_pk_mul_f32 v[76:77], v[64:65], v[76:77]
	v_pk_mul_f32 v[64:65], v[64:65], v[64:65]
	v_pk_mul_f32 v[78:79], v[66:67], v[78:79]
	v_pk_mul_f32 v[66:67], v[66:67], v[66:67]
	v_add_f32_e32 v64, v64, v65
	v_add_f32_e32 v64, v66, v64
	v_add_f32_e32 v64, v67, v64
	v_cvt_pk_bf16_f32 v76, v76, v77
	v_cvt_pk_bf16_f32 v77, v78, v79
	v_add_f32_dpp v64, v64, v64 quad_perm:[1,0,3,2] row_mask:0xf bank_mask:0xf bound_ctrl:1
	global_store_dwordx2 v[74:75], v[76:77], off
	s_nop 0
	v_add_f32_dpp v64, v64, v64 quad_perm:[2,3,0,1] row_mask:0xf bank_mask:0xf bound_ctrl:1
	s_nop 1
	v_add_f32_dpp v64, v64, v64 row_half_mirror row_mask:0xf bank_mask:0xf bound_ctrl:1
	s_nop 1
	v_mov_b32_dpp v65, v64 row_mirror row_mask:0xf bank_mask:0xf bound_ctrl:1
	s_and_saveexec_b64 s[4:5], s[40:41]
	s_cbranch_execz .LBB0_1235
	v_ashrrev_i32_e32 v97, 31, v96
	v_lshl_add_u64 v[66:67], s[48:49], 0, v[68:69]
	v_lshl_add_u64 v[74:75], v[96:97], 0, v[128:129]
	v_lshl_add_u64 v[66:67], v[74:75], 2, v[66:67]
	v_add_f32_e32 v64, v64, v65
	global_store_dword v[66:67], v64, off offset:32

.LBB0_1236:
	v_or_b32_e32 v74, 12, v128
	v_or_b32_e32 v76, v96, v74
	v_ashrrev_i32_e32 v77, 31, v76
	v_lshlrev_b64 v[64:65], 12, v[76:77]
	v_lshl_add_u64 v[64:65], s[42:43], 0, v[64:65]
	v_lshl_add_u64 v[88:89], v[98:99], 2, v[64:65]
	s_movk_i32 s4, 0x1000
	v_cmp_gt_i32_e32 vcc, s4, v76
	s_nop 1
	v_cndmask_b32_e32 v73, v71, v102, vcc
	v_and_b32_e32 v73, 1, v73
	v_cmp_eq_u32_e32 vcc, 1, v73
	s_nop 1
	v_cndmask_b32_e64 v73, v171, 0, vcc
	v_add_u32_e32 v73, v103, v73
	ds_read_b128 v[78:81], v86 offset:3264
	ds_read_b128 v[82:85], v73
	s_and_b64 vcc, exec, s[0:1]
	s_waitcnt lgkmcnt(0)
	v_pk_fma_f32 v[66:67], v[80:81], v[84:85], v[212:213]
	v_pk_fma_f32 v[64:65], v[78:79], v[82:83], v[210:211]
	global_store_dwordx4 v[88:89], v[64:67], off
	s_cbranch_vccnz .LBB0_1240
	ds_read_b128 v[78:81], v73 offset:2048
	v_lshlrev_b64 v[76:77], 10, v[76:77]
	v_lshl_add_u64 v[76:77], v[76:77], 1, s[44:45]
	v_lshl_add_u64 v[76:77], v[98:99], 1, v[76:77]
	s_waitcnt lgkmcnt(0)
	v_pk_mul_f32 v[78:79], v[64:65], v[78:79]
	v_pk_mul_f32 v[64:65], v[64:65], v[64:65]
	v_pk_mul_f32 v[80:81], v[66:67], v[80:81]
	v_pk_mul_f32 v[66:67], v[66:67], v[66:67]
	v_add_f32_e32 v64, v64, v65
	v_add_f32_e32 v64, v66, v64
	v_add_f32_e32 v64, v67, v64
	v_cvt_pk_bf16_f32 v78, v78, v79
	v_cvt_pk_bf16_f32 v79, v80, v81
	v_add_f32_dpp v64, v64, v64 quad_perm:[1,0,3,2] row_mask:0xf bank_mask:0xf bound_ctrl:1
	global_store_dwordx2 v[76:77], v[78:79], off
	s_nop 0
	v_add_f32_dpp v64, v64, v64 quad_perm:[2,3,0,1] row_mask:0xf bank_mask:0xf bound_ctrl:1
	s_nop 1
	v_add_f32_dpp v64, v64, v64 row_half_mirror row_mask:0xf bank_mask:0xf bound_ctrl:1
	s_nop 1
	v_mov_b32_dpp v65, v64 row_mirror row_mask:0xf bank_mask:0xf bound_ctrl:1
	s_and_saveexec_b64 s[4:5], s[40:41]
	s_cbranch_execz .LBB0_1239
	v_ashrrev_i32_e32 v97, 31, v96
	v_lshl_add_u64 v[66:67], s[48:49], 0, v[68:69]
	v_lshl_add_u64 v[76:77], v[96:97], 0, v[128:129]
	v_lshl_add_u64 v[66:67], v[76:77], 2, v[66:67]
	v_add_f32_e32 v64, v64, v65
	global_store_dword v[66:67], v64, off offset:48

.LBB0_1240:
	v_or_b32_e32 v76, 16, v128
	v_or_b32_e32 v78, v96, v76
	v_ashrrev_i32_e32 v79, 31, v78
	v_lshlrev_b64 v[64:65], 12, v[78:79]
	v_lshl_add_u64 v[64:65], s[42:43], 0, v[64:65]
	v_lshl_add_u64 v[84:85], v[98:99], 2, v[64:65]
	s_movk_i32 s4, 0x1000
	v_cmp_gt_i32_e32 vcc, s4, v78
	s_nop 1
	v_cndmask_b32_e32 v73, v71, v102, vcc
	v_and_b32_e32 v73, 1, v73
	v_cmp_eq_u32_e32 vcc, 1, v73
	s_nop 1
	v_cndmask_b32_e64 v73, v171, 0, vcc
	v_add_u32_e32 v73, v103, v73
	ds_read_b128 v[80:83], v86 offset:4352
	ds_read_b128 v[88:91], v73
	s_and_b64 vcc, exec, s[0:1]
	s_waitcnt lgkmcnt(0)
	v_pk_fma_f32 v[66:67], v[82:83], v[90:91], v[216:217]
	v_pk_fma_f32 v[64:65], v[80:81], v[88:89], v[214:215]
	global_store_dwordx4 v[84:85], v[64:67], off
	s_cbranch_vccnz .LBB0_1244
	ds_read_b128 v[80:83], v73 offset:2048
	v_lshlrev_b64 v[78:79], 10, v[78:79]
	v_lshl_add_u64 v[78:79], v[78:79], 1, s[44:45]
	v_lshl_add_u64 v[78:79], v[98:99], 1, v[78:79]
	s_waitcnt lgkmcnt(0)
	v_pk_mul_f32 v[80:81], v[64:65], v[80:81]
	v_pk_mul_f32 v[64:65], v[64:65], v[64:65]
	v_pk_mul_f32 v[82:83], v[66:67], v[82:83]
	v_pk_mul_f32 v[66:67], v[66:67], v[66:67]
	v_add_f32_e32 v64, v64, v65
	v_add_f32_e32 v64, v66, v64
	v_add_f32_e32 v64, v67, v64
	v_cvt_pk_bf16_f32 v80, v80, v81
	v_cvt_pk_bf16_f32 v81, v82, v83
	v_add_f32_dpp v64, v64, v64 quad_perm:[1,0,3,2] row_mask:0xf bank_mask:0xf bound_ctrl:1
	global_store_dwordx2 v[78:79], v[80:81], off
	s_nop 0
	v_add_f32_dpp v64, v64, v64 quad_perm:[2,3,0,1] row_mask:0xf bank_mask:0xf bound_ctrl:1
	s_nop 1
	v_add_f32_dpp v64, v64, v64 row_half_mirror row_mask:0xf bank_mask:0xf bound_ctrl:1
	s_nop 1
	v_mov_b32_dpp v65, v64 row_mirror row_mask:0xf bank_mask:0xf bound_ctrl:1
	s_and_saveexec_b64 s[4:5], s[40:41]
	s_cbranch_execz .LBB0_1243
	v_ashrrev_i32_e32 v97, 31, v96
	v_lshl_add_u64 v[66:67], s[48:49], 0, v[68:69]
	v_lshl_add_u64 v[78:79], v[96:97], 0, v[128:129]
	v_lshl_add_u64 v[66:67], v[78:79], 2, v[66:67]
	v_add_f32_e32 v64, v64, v65
	global_store_dword v[66:67], v64, off offset:64

.LBB0_1244:
	v_or_b32_e32 v78, 20, v128
	v_or_b32_e32 v80, v96, v78
	v_ashrrev_i32_e32 v81, 31, v80
	v_lshlrev_b64 v[64:65], 12, v[80:81]
	v_lshl_add_u64 v[64:65], s[42:43], 0, v[64:65]
	v_lshl_add_u64 v[92:93], v[98:99], 2, v[64:65]
	s_movk_i32 s4, 0x1000
	v_cmp_gt_i32_e32 vcc, s4, v80
	s_nop 1
	v_cndmask_b32_e32 v73, v71, v102, vcc
	v_and_b32_e32 v73, 1, v73
	v_cmp_eq_u32_e32 vcc, 1, v73
	s_nop 1
	v_cndmask_b32_e64 v73, v171, 0, vcc
	v_add_u32_e32 v73, v103, v73
	ds_read_b128 v[82:85], v86 offset:5440
	ds_read_b128 v[88:91], v73
	s_and_b64 vcc, exec, s[0:1]
	s_waitcnt lgkmcnt(0)
	v_pk_fma_f32 v[66:67], v[84:85], v[90:91], v[220:221]
	v_pk_fma_f32 v[64:65], v[82:83], v[88:89], v[218:219]
	global_store_dwordx4 v[92:93], v[64:67], off
	s_cbranch_vccnz .LBB0_1248
	ds_read_b128 v[82:85], v73 offset:2048
	v_lshlrev_b64 v[80:81], 10, v[80:81]
	v_lshl_add_u64 v[80:81], v[80:81], 1, s[44:45]
	v_lshl_add_u64 v[80:81], v[98:99], 1, v[80:81]
	s_waitcnt lgkmcnt(0)
	v_pk_mul_f32 v[82:83], v[64:65], v[82:83]
	v_pk_mul_f32 v[64:65], v[64:65], v[64:65]
	v_pk_mul_f32 v[84:85], v[66:67], v[84:85]
	v_pk_mul_f32 v[66:67], v[66:67], v[66:67]
	v_add_f32_e32 v64, v64, v65
	v_add_f32_e32 v64, v66, v64
	v_add_f32_e32 v64, v67, v64
	v_cvt_pk_bf16_f32 v82, v82, v83
	v_cvt_pk_bf16_f32 v83, v84, v85
	v_add_f32_dpp v64, v64, v64 quad_perm:[1,0,3,2] row_mask:0xf bank_mask:0xf bound_ctrl:1
	global_store_dwordx2 v[80:81], v[82:83], off
	s_nop 0
	v_add_f32_dpp v64, v64, v64 quad_perm:[2,3,0,1] row_mask:0xf bank_mask:0xf bound_ctrl:1
	s_nop 1
	v_add_f32_dpp v64, v64, v64 row_half_mirror row_mask:0xf bank_mask:0xf bound_ctrl:1
	s_nop 1
	v_mov_b32_dpp v65, v64 row_mirror row_mask:0xf bank_mask:0xf bound_ctrl:1
	s_and_saveexec_b64 s[4:5], s[40:41]
	s_cbranch_execz .LBB0_1247
	v_ashrrev_i32_e32 v97, 31, v96
	v_lshl_add_u64 v[66:67], s[48:49], 0, v[68:69]
	v_lshl_add_u64 v[80:81], v[96:97], 0, v[128:129]
	v_lshl_add_u64 v[66:67], v[80:81], 2, v[66:67]
	v_add_f32_e32 v64, v64, v65
	global_store_dword v[66:67], v64, off offset:80

.LBB0_1248:
	v_or_b32_e32 v80, 24, v128
	v_or_b32_e32 v82, v96, v80
	v_ashrrev_i32_e32 v83, 31, v82
	v_lshlrev_b64 v[64:65], 12, v[82:83]
	v_lshl_add_u64 v[64:65], s[42:43], 0, v[64:65]
	v_lshl_add_u64 v[84:85], v[98:99], 2, v[64:65]
	s_movk_i32 s4, 0x1000
	v_cmp_gt_i32_e32 vcc, s4, v82
	s_nop 1
	v_cndmask_b32_e32 v73, v71, v102, vcc
	v_and_b32_e32 v73, 1, v73
	v_cmp_eq_u32_e32 vcc, 1, v73
	s_nop 1
	v_cndmask_b32_e64 v73, v171, 0, vcc
	v_add_u32_e32 v73, v103, v73
	ds_read_b128 v[88:91], v86 offset:6528
	ds_read_b128 v[92:95], v73
	s_and_b64 vcc, exec, s[0:1]
	s_waitcnt lgkmcnt(0)
	v_pk_fma_f32 v[66:67], v[90:91], v[94:95], v[224:225]
	v_pk_fma_f32 v[64:65], v[88:89], v[92:93], v[222:223]
	global_store_dwordx4 v[84:85], v[64:67], off
	s_cbranch_vccnz .LBB0_1252
	ds_read_b128 v[88:91], v73 offset:2048
	v_lshlrev_b64 v[82:83], 10, v[82:83]
	v_lshl_add_u64 v[82:83], v[82:83], 1, s[44:45]
	v_lshl_add_u64 v[82:83], v[98:99], 1, v[82:83]
	s_waitcnt lgkmcnt(0)
	v_pk_mul_f32 v[88:89], v[64:65], v[88:89]
	v_pk_mul_f32 v[64:65], v[64:65], v[64:65]
	v_pk_mul_f32 v[84:85], v[66:67], v[90:91]
	v_pk_mul_f32 v[66:67], v[66:67], v[66:67]
	v_add_f32_e32 v64, v64, v65
	v_add_f32_e32 v64, v66, v64
	v_add_f32_e32 v64, v67, v64
	v_cvt_pk_bf16_f32 v88, v88, v89
	v_cvt_pk_bf16_f32 v89, v84, v85
	v_add_f32_dpp v64, v64, v64 quad_perm:[1,0,3,2] row_mask:0xf bank_mask:0xf bound_ctrl:1
	global_store_dwordx2 v[82:83], v[88:89], off
	s_nop 0
	v_add_f32_dpp v64, v64, v64 quad_perm:[2,3,0,1] row_mask:0xf bank_mask:0xf bound_ctrl:1
	s_nop 1
	v_add_f32_dpp v64, v64, v64 row_half_mirror row_mask:0xf bank_mask:0xf bound_ctrl:1
	s_nop 1
	v_mov_b32_dpp v65, v64 row_mirror row_mask:0xf bank_mask:0xf bound_ctrl:1
	s_and_saveexec_b64 s[4:5], s[40:41]
	s_cbranch_execz .LBB0_1251
	v_ashrrev_i32_e32 v97, 31, v96
	v_lshl_add_u64 v[66:67], s[48:49], 0, v[68:69]
	v_lshl_add_u64 v[82:83], v[96:97], 0, v[128:129]
	v_lshl_add_u64 v[66:67], v[82:83], 2, v[66:67]
	v_add_f32_e32 v64, v64, v65
	global_store_dword v[66:67], v64, off offset:96

.LBB0_1252:
	v_or_b32_e32 v82, 28, v128
	v_or_b32_e32 v84, v96, v82
	v_ashrrev_i32_e32 v85, 31, v84
	v_lshlrev_b64 v[64:65], 12, v[84:85]
	v_lshl_add_u64 v[64:65], s[42:43], 0, v[64:65]
	v_lshl_add_u64 v[100:101], v[98:99], 2, v[64:65]
	s_movk_i32 s4, 0x1000
	v_cmp_gt_i32_e32 vcc, s4, v84
	s_nop 1
	v_cndmask_b32_e32 v71, v71, v102, vcc
	v_and_b32_e32 v71, 1, v71
	v_cmp_eq_u32_e32 vcc, 1, v71
	s_nop 1
	v_cndmask_b32_e64 v71, v171, 0, vcc
	v_add_u32_e32 v71, v103, v71
	ds_read_b128 v[88:91], v86 offset:7616
	ds_read_b128 v[92:95], v71
	s_and_b64 vcc, exec, s[0:1]
	s_waitcnt lgkmcnt(0)
	v_pk_fma_f32 v[66:67], v[90:91], v[94:95], v[228:229]
	v_pk_fma_f32 v[64:65], v[88:89], v[92:93], v[226:227]
	global_store_dwordx4 v[100:101], v[64:67], off
	s_cbranch_vccnz .LBB0_1256
	ds_read_b128 v[88:91], v71 offset:2048
	v_lshlrev_b64 v[84:85], 10, v[84:85]
	v_lshl_add_u64 v[84:85], v[84:85], 1, s[44:45]
	v_lshl_add_u64 v[84:85], v[98:99], 1, v[84:85]
	s_waitcnt lgkmcnt(0)
	v_pk_mul_f32 v[88:89], v[64:65], v[88:89]
	v_pk_mul_f32 v[64:65], v[64:65], v[64:65]
	v_pk_mul_f32 v[90:91], v[66:67], v[90:91]
	v_pk_mul_f32 v[66:67], v[66:67], v[66:67]
	v_add_f32_e32 v64, v64, v65
	v_add_f32_e32 v64, v66, v64
	v_add_f32_e32 v64, v67, v64
	v_cvt_pk_bf16_f32 v88, v88, v89
	v_cvt_pk_bf16_f32 v89, v90, v91
	v_add_f32_dpp v64, v64, v64 quad_perm:[1,0,3,2] row_mask:0xf bank_mask:0xf bound_ctrl:1
	global_store_dwordx2 v[84:85], v[88:89], off
	s_nop 0
	v_add_f32_dpp v64, v64, v64 quad_perm:[2,3,0,1] row_mask:0xf bank_mask:0xf bound_ctrl:1
	s_nop 1
	v_add_f32_dpp v64, v64, v64 row_half_mirror row_mask:0xf bank_mask:0xf bound_ctrl:1
	s_nop 1
	v_mov_b32_dpp v65, v64 row_mirror row_mask:0xf bank_mask:0xf bound_ctrl:1
	s_and_saveexec_b64 s[4:5], s[40:41]
	s_cbranch_execz .LBB0_1255
	v_ashrrev_i32_e32 v97, 31, v96
	v_lshl_add_u64 v[66:67], s[48:49], 0, v[68:69]
	v_lshl_add_u64 v[84:85], v[96:97], 0, v[128:129]
	v_lshl_add_u64 v[66:67], v[84:85], 2, v[66:67]
	v_add_f32_e32 v64, v64, v65
	global_store_dword v[66:67], v64, off offset:112

.LBB0_1433:
	s_waitcnt vmcnt(0)
	ds_write_b32 v2, v246
	v_ashrrev_i32_e32 v103, 6, v100
	v_lshrrev_b32_e32 v0, 30, v103
	v_add_u32_e32 v0, v103, v0
	v_ashrrev_i32_e32 v10, 2, v0
	v_mul_i32_i24_e32 v0, 4, v10
	v_ashrrev_i32_e32 v6, 3, v100
	v_sub_u32_e32 v11, v103, v0
	v_lshrrev_b32_e32 v13, 4, v100
	v_add_u32_e32 v0, s4, v6
	v_xor_b32_e32 v7, v13, v100
	v_ashrrev_i32_e32 v1, 31, v0
	v_lshlrev_b64 v[0:1], 13, v[0:1]
	v_lshlrev_b32_e32 v7, 4, v7
	v_lshlrev_b32_e32 v109, 4, v100
	s_and_b32 s8, s2, 0xffffff00
	v_lshl_add_u64 v[4:5], s[52:53], 0, v[0:1]
	v_and_b32_e32 v128, 0x70, v7
	v_readfirstlane_b32 s2, v109
	v_add_u32_e32 v14, 0x2000, v109
	v_lshl_add_u64 v[4:5], v[4:5], 0, v[128:129]
	s_mov_b32 m0, s2
	v_readfirstlane_b32 s2, v14
	ds_write_b32 v2, v3 offset:2048
	v_lshl_add_u64 v[2:3], v[4:5], 0, s[16:17]
	s_mov_b32 m0, s2
	v_add_u32_e32 v6, s8, v6
	v_lshl_add_u64 v[2:3], v[4:5], 0, s[20:21]
	v_add_u32_e32 v4, 0x4000, v109
	v_ashrrev_i32_e32 v7, 31, v6
	v_readfirstlane_b32 s2, v4
	s_mov_b32 m0, s2
	v_lshlrev_b64 v[6:7], 13, v[6:7]
	v_add_u32_e32 v2, 0x6000, v109
	v_lshl_add_u64 v[8:9], s[48:49], 0, v[6:7]
	v_readfirstlane_b32 s2, v2
	v_add_u32_e32 v4, 0x8000, v109
	v_lshl_add_u64 v[8:9], v[8:9], 0, v[128:129]
	s_mov_b32 m0, s2
	v_readfirstlane_b32 s2, v4
	v_add_u32_e32 v4, 0xa000, v109
	v_lshl_add_u64 v[2:3], v[8:9], 0, s[16:17]
	s_mov_b32 m0, s2
	v_readfirstlane_b32 s2, v4
	v_lshl_add_u64 v[2:3], v[8:9], 0, s[20:21]
	s_mov_b32 m0, s2
	s_mov_b64 s[2:3], 0x180000
	v_add_u32_e32 v4, 0xc000, v109
	v_lshl_add_u64 v[2:3], v[8:9], 0, s[2:3]
	v_readfirstlane_b32 s2, v4
	s_mov_b32 m0, s2
	v_and_b32_e32 v102, 31, v100
	v_lshlrev_b32_e32 v105, 6, v11
	v_or_b32_e32 v3, v105, v102
	v_mul_i32_i24_e32 v106, 0x60, v10
	v_bfe_u32 v12, v100, 5, 1
	v_lshrrev_b32_e32 v104, 1, v100
	v_lshlrev_b32_e32 v112, 7, v3
	v_or_b32_e32 v3, v106, v102
	v_bfe_u32 v2, v100, 1, 3
	v_lshlrev_b32_e32 v113, 7, v3
	v_bitop3_b32 v3, v12, v104, 7 bitop3:0x78
	v_lshlrev_b32_e32 v111, 4, v3
	v_bitop3_b32 v3, v12, v2, 2 bitop3:0x36
	v_lshlrev_b32_e32 v110, 4, v3
	v_bitop3_b32 v3, v12, v2, 4 bitop3:0x36
	v_bitop3_b32 v2, v12, v2, 6 bitop3:0x36
	v_lshlrev_b32_e32 v107, 4, v2
	v_bitop3_b32 v2, v13, 7, v100 bitop3:0x48
	v_lshlrev_b32_e32 v2, 4, v2
	v_or_b32_e32 v6, v6, v2
	v_or_b32_e32 v0, v0, v2
	v_and_b32_e32 v101, 63, v100
	v_lshlrev_b32_e32 v108, 4, v3
	v_add_u32_e32 v114, 0x6000, v112
	v_lshl_add_u64 v[96:97], s[60:61], 0, v[6:7]
	v_lshl_add_u64 v[98:99], s[14:15], 0, v[0:1]
	s_mov_b32 s7, 0
	s_mov_b64 s[2:3], 0
	v_mov_b32_e32 v33, v32
	v_mov_b32_e32 v34, v32
	v_mov_b32_e32 v35, v32
	v_mov_b32_e32 v36, v32
	v_mov_b32_e32 v37, v32
	v_mov_b32_e32 v38, v32
	v_mov_b32_e32 v39, v32
	v_mov_b32_e32 v40, v32
	v_mov_b32_e32 v41, v32
	v_mov_b32_e32 v42, v32
	v_mov_b32_e32 v43, v32
	v_mov_b32_e32 v44, v32
	v_mov_b32_e32 v45, v32
	v_mov_b32_e32 v46, v32
	v_mov_b32_e32 v47, v32
	v_mov_b32_e32 v64, v32
	v_mov_b32_e32 v65, v32
	v_mov_b32_e32 v66, v32
	v_mov_b32_e32 v67, v32
	v_mov_b32_e32 v68, v32
	v_mov_b32_e32 v69, v32
	v_mov_b32_e32 v70, v32
	v_mov_b32_e32 v71, v32
	v_mov_b32_e32 v72, v32
	v_mov_b32_e32 v73, v32
	v_mov_b32_e32 v74, v32
	v_mov_b32_e32 v75, v32
	v_mov_b32_e32 v76, v32
	v_mov_b32_e32 v77, v32
	v_mov_b32_e32 v78, v32
	v_mov_b32_e32 v79, v32
	v_mov_b32_e32 v0, v32
	v_mov_b32_e32 v1, v32
	v_mov_b32_e32 v2, v32
	v_mov_b32_e32 v3, v32
	v_mov_b32_e32 v4, v32
	v_mov_b32_e32 v5, v32
	v_mov_b32_e32 v6, v32
	v_mov_b32_e32 v7, v32
	v_mov_b32_e32 v8, v32
	v_mov_b32_e32 v9, v32
	v_mov_b32_e32 v10, v32
	v_mov_b32_e32 v11, v32
	v_mov_b32_e32 v12, v32
	v_mov_b32_e32 v13, v32
	v_mov_b32_e32 v14, v32
	v_mov_b32_e32 v15, v32
	v_mov_b32_e32 v80, v32
	v_mov_b32_e32 v81, v32
	v_mov_b32_e32 v82, v32
	v_mov_b32_e32 v83, v32
	v_mov_b32_e32 v84, v32
	v_mov_b32_e32 v85, v32
	v_mov_b32_e32 v86, v32
	v_mov_b32_e32 v87, v32
	v_mov_b32_e32 v88, v32
	v_mov_b32_e32 v89, v32
	v_mov_b32_e32 v90, v32
	v_mov_b32_e32 v91, v32
	v_mov_b32_e32 v92, v32
	v_mov_b32_e32 v93, v32
	v_mov_b32_e32 v94, v32
	v_mov_b32_e32 v95, v32
	v_mov_b32_e32 v48, v32
	v_mov_b32_e32 v49, v32
	v_mov_b32_e32 v50, v32
	v_mov_b32_e32 v51, v32
	v_mov_b32_e32 v52, v32
	v_mov_b32_e32 v53, v32
	v_mov_b32_e32 v54, v32
	v_mov_b32_e32 v55, v32
	v_mov_b32_e32 v56, v32
	v_mov_b32_e32 v57, v32
	v_mov_b32_e32 v58, v32
	v_mov_b32_e32 v59, v32
	v_mov_b32_e32 v60, v32
	v_mov_b32_e32 v61, v32
	v_mov_b32_e32 v62, v32
	v_mov_b32_e32 v63, v32
	v_mov_b32_e32 v16, v32
	v_mov_b32_e32 v17, v32
	v_mov_b32_e32 v18, v32
	v_mov_b32_e32 v19, v32
	v_mov_b32_e32 v20, v32
	v_mov_b32_e32 v21, v32
	v_mov_b32_e32 v22, v32
	v_mov_b32_e32 v23, v32
	v_mov_b32_e32 v24, v32
	v_mov_b32_e32 v25, v32
	v_mov_b32_e32 v26, v32
	v_mov_b32_e32 v27, v32
	v_mov_b32_e32 v28, v32
	v_mov_b32_e32 v29, v32
	v_mov_b32_e32 v30, v32
	v_mov_b32_e32 v31, v32
	v_add_u32_e32 v243, s4, v106
	v_lshrrev_b32_e32 v244, 4, v101
	v_or_b32_e32 v243, v243, v244
	v_and_b32_e32 v244, 15, v100
	v_add_u32_e32 v245, s8, v105
	v_lshl_or_b32 v244, v244, 2, v245
	v_lshlrev_b32_e32 v243, 12, v243
	v_lshl_add_u32 v243, v244, 2, v243
	global_load_dwordx4 v[198:201], v243, s[40:41]
	v_add_u32_e32 v243, 0x4000, v243
	global_load_dwordx4 v[202:205], v243, s[40:41]
	v_add_u32_e32 v243, 0x4000, v243
	global_load_dwordx4 v[206:209], v243, s[40:41]
	v_add_u32_e32 v243, 0x4000, v243
	global_load_dwordx4 v[210:213], v243, s[40:41]
	v_add_u32_e32 v243, 0x4000, v243
	global_load_dwordx4 v[214:217], v243, s[40:41]
	v_add_u32_e32 v243, 0x4000, v243
	global_load_dwordx4 v[218:221], v243, s[40:41]
	v_add_u32_e32 v243, 0x4000, v243
	global_load_dwordx4 v[222:225], v243, s[40:41]
	v_add_u32_e32 v243, 0x4000, v243
	global_load_dwordx4 v[226:229], v243, s[40:41]
.LBB0_1434:
	s_add_i32 s9, s7, 1
	s_bitcmp1_b32 s9, 0
	s_cselect_b32 s10, 0xe000, 0
	v_add_u32_e32 v115, s10, v109
	v_lshl_add_u64 v[116:117], v[98:99], 0, s[2:3]
	s_mov_b64 s[10:11], 0x9f94080
	v_lshl_add_u64 v[118:119], v[116:117], 0, s[10:11]
	v_readfirstlane_b32 s10, v115
	s_mov_b32 m0, s10
	s_mov_b64 s[10:11], 0xa014080
	v_add_u32_e32 v120, 0x2000, v115
	s_waitcnt vmcnt(0)
	s_waitcnt vmcnt(0) lgkmcnt(0)
	s_barrier
	global_load_lds_dwordx4 v[118:119], off
	v_lshl_add_u64 v[118:119], v[116:117], 0, s[10:11]
	v_readfirstlane_b32 s10, v120
	s_mov_b32 m0, s10
	s_mov_b64 s[10:11], 0xa094080
	global_load_lds_dwordx4 v[118:119], off
	v_add_u32_e32 v118, 0x4000, v115
	v_lshl_add_u64 v[116:117], v[116:117], 0, s[10:11]
	v_readfirstlane_b32 s10, v118
	s_mov_b32 m0, s10
	s_mov_b64 s[10:11], 0x3314080
	global_load_lds_dwordx4 v[116:117], off
	v_lshl_add_u64 v[116:117], v[96:97], 0, s[2:3]
	v_add_u32_e32 v120, 0x6000, v115
	v_lshl_add_u64 v[118:119], v[116:117], 0, s[10:11]
	v_readfirstlane_b32 s10, v120
	s_mov_b32 m0, s10
	s_mov_b64 s[10:11], 0x3394080
	v_add_u32_e32 v120, 0x8000, v115
	global_load_lds_dwordx4 v[118:119], off
	v_lshl_add_u64 v[118:119], v[116:117], 0, s[10:11]
	v_readfirstlane_b32 s10, v120
	s_mov_b32 m0, s10
	s_mov_b64 s[10:11], 0x3414080
	v_add_u32_e32 v120, 0xa000, v115
	global_load_lds_dwordx4 v[118:119], off
	v_lshl_add_u64 v[118:119], v[116:117], 0, s[10:11]
	v_readfirstlane_b32 s10, v120
	s_mov_b32 m0, s10
	s_mov_b64 s[10:11], 0x3494080
	v_add_u32_e32 v115, 0xc000, v115
	v_lshl_add_u64 v[116:117], v[116:117], 0, s[10:11]
	v_readfirstlane_b32 s10, v115
	global_load_lds_dwordx4 v[118:119], off
	s_mov_b32 m0, s10
	s_nop 0
	global_load_lds_dwordx4 v[116:117], off
	s_bitcmp1_b32 s7, 0
	s_cselect_b32 s7, 0xe000, 0
	v_add_u32_e32 v115, s7, v114
	v_add_u32_e32 v120, v115, v111
	ds_read_b128 v[116:119], v120 offset:0
	v_add_u32_e32 v128, s7, v113
	ds_read_b128 v[120:123], v120 offset:0x1000
	v_add_u32_e32 v134, v128, v111
	ds_read_b128 v[124:127], v134 offset:0
	ds_read_b128 v[130:133], v134 offset:0x1000
	ds_read_b128 v[134:137], v134 offset:0x2000
	v_add_u32_e32 v148, v115, v110
	ds_read_b128 v[144:147], v148 offset:0
	ds_read_b128 v[148:151], v148 offset:0x1000
	v_add_u32_e32 v152, v128, v110
	ds_read_b128 v[182:185], v152 offset:0
	ds_read_b128 v[186:189], v152 offset:0x1000
	ds_read_b128 v[190:193], v152 offset:0x2000
	s_waitcnt lgkmcnt(5)
	s_nop 0
	v_mfma_f32_32x32x16_bf16 v[64:79], v[116:119], v[124:127], v[64:79]
	v_mfma_f32_32x32x16_bf16 v[32:47], v[116:119], v[130:133], v[32:47]
	v_mfma_f32_32x32x16_bf16 v[0:15], v[116:119], v[134:137], v[0:15]
	v_mfma_f32_32x32x16_bf16 v[80:95], v[120:123], v[124:127], v[80:95]
	v_mfma_f32_32x32x16_bf16 v[48:63], v[120:123], v[130:133], v[48:63]
	v_mfma_f32_32x32x16_bf16 v[16:31], v[120:123], v[134:137], v[16:31]
	v_add_u32_e32 v120, v115, v108
	ds_read_b128 v[116:119], v120 offset:0
	ds_read_b128 v[120:123], v120 offset:0x1000
	v_add_u32_e32 v134, v128, v108
	ds_read_b128 v[124:127], v134 offset:0
	ds_read_b128 v[130:133], v134 offset:0x1000
	ds_read_b128 v[134:137], v134 offset:0x2000
	s_waitcnt lgkmcnt(5)
	s_nop 0
	v_mfma_f32_32x32x16_bf16 v[64:79], v[144:147], v[182:185], v[64:79]
	v_mfma_f32_32x32x16_bf16 v[32:47], v[144:147], v[186:189], v[32:47]
	v_mfma_f32_32x32x16_bf16 v[0:15], v[144:147], v[190:193], v[0:15]
	v_mfma_f32_32x32x16_bf16 v[80:95], v[148:151], v[182:185], v[80:95]
	v_mfma_f32_32x32x16_bf16 v[48:63], v[148:151], v[186:189], v[48:63]
	v_mfma_f32_32x32x16_bf16 v[16:31], v[148:151], v[190:193], v[16:31]
	v_add_u32_e32 v115, v115, v107
	ds_read_b128 v[144:147], v115 offset:0
	ds_read_b128 v[148:151], v115 offset:0x1000
	v_add_u32_e32 v115, v128, v107
	ds_read_b128 v[182:185], v115 offset:0
	ds_read_b128 v[186:189], v115 offset:0x1000
	ds_read_b128 v[190:193], v115 offset:0x2000
	s_waitcnt lgkmcnt(5)
	s_nop 0
	v_mfma_f32_32x32x16_bf16 v[64:79], v[116:119], v[124:127], v[64:79]
	v_mfma_f32_32x32x16_bf16 v[32:47], v[116:119], v[130:133], v[32:47]
	v_mfma_f32_32x32x16_bf16 v[0:15], v[116:119], v[134:137], v[0:15]
	v_mfma_f32_32x32x16_bf16 v[80:95], v[120:123], v[124:127], v[80:95]
	v_mfma_f32_32x32x16_bf16 v[48:63], v[120:123], v[130:133], v[48:63]
	v_mfma_f32_32x32x16_bf16 v[16:31], v[120:123], v[134:137], v[16:31]
	s_waitcnt lgkmcnt(0)
	s_nop 0
	v_mfma_f32_32x32x16_bf16 v[64:79], v[144:147], v[182:185], v[64:79]
	v_mfma_f32_32x32x16_bf16 v[32:47], v[144:147], v[186:189], v[32:47]
	v_mfma_f32_32x32x16_bf16 v[0:15], v[144:147], v[190:193], v[0:15]
	v_mfma_f32_32x32x16_bf16 v[80:95], v[148:151], v[182:185], v[80:95]
	v_mfma_f32_32x32x16_bf16 v[48:63], v[148:151], v[186:189], v[48:63]
	v_mfma_f32_32x32x16_bf16 v[16:31], v[148:151], v[190:193], v[16:31]
	s_add_u32 s2, s2, 0x80
	s_addc_u32 s3, s3, 0
	s_cmpk_eq_i32 s2, 0x1f80
	s_mov_b32 s7, s9
	s_cbranch_scc0 .LBB0_1434
	s_waitcnt vmcnt(0)
	s_waitcnt vmcnt(0) lgkmcnt(0)
	s_barrier
	v_add_u32_e32 v109, 0x14000, v112
	v_add_u32_e32 v112, v109, v111
	ds_read_b128 v[96:99], v112 offset:0
	v_add_u32_e32 v128, 0xe000, v113
	ds_read_b128 v[112:115], v112 offset:0x1000
	v_add_u32_e32 v111, v128, v111
	ds_read_b128 v[116:119], v111 offset:0
	ds_read_b128 v[120:123], v111 offset:0x1000
	ds_read_b128 v[124:127], v111 offset:0x2000
	v_add_u32_e32 v111, v109, v110
	ds_read_b128 v[130:133], v111 offset:0
	ds_read_b128 v[134:137], v111 offset:0x1000
	v_add_u32_e32 v110, v128, v110
	ds_read_b128 v[144:147], v110 offset:0
	ds_read_b128 v[148:151], v110 offset:0x1000
	ds_read_b128 v[182:185], v110 offset:0x2000
	s_waitcnt lgkmcnt(5)
	s_nop 0
	v_mfma_f32_32x32x16_bf16 v[64:79], v[96:99], v[116:119], v[64:79]
	v_mfma_f32_32x32x16_bf16 v[32:47], v[96:99], v[120:123], v[32:47]
	v_mfma_f32_32x32x16_bf16 v[0:15], v[96:99], v[124:127], v[0:15]
	v_mfma_f32_32x32x16_bf16 v[48:63], v[112:115], v[120:123], v[48:63]
	v_mfma_f32_32x32x16_bf16 v[16:31], v[112:115], v[124:127], v[16:31]
	v_mfma_f32_32x32x16_bf16 v[80:95], v[112:115], v[116:119], v[80:95]
	v_add_u32_e32 v110, v109, v108
	ds_read_b128 v[96:99], v110 offset:0
	ds_read_b128 v[110:113], v110 offset:0x1000
	v_add_u32_e32 v108, v128, v108
	ds_read_b128 v[114:117], v108 offset:0
	ds_read_b128 v[118:121], v108 offset:0x1000
	ds_read_b128 v[122:125], v108 offset:0x2000
	s_waitcnt lgkmcnt(5)
	s_nop 0
	v_mfma_f32_32x32x16_bf16 v[64:79], v[130:133], v[144:147], v[64:79]
	v_mfma_f32_32x32x16_bf16 v[32:47], v[130:133], v[148:151], v[32:47]
	v_mfma_f32_32x32x16_bf16 v[0:15], v[130:133], v[182:185], v[0:15]
	v_mfma_f32_32x32x16_bf16 v[48:63], v[134:137], v[148:151], v[48:63]
	v_mfma_f32_32x32x16_bf16 v[16:31], v[134:137], v[182:185], v[16:31]
	v_mfma_f32_32x32x16_bf16 v[80:95], v[134:137], v[144:147], v[80:95]
	v_add_u32_e32 v108, v109, v107
	ds_read_b128 v[130:133], v108 offset:0
	ds_read_b128 v[134:137], v108 offset:0x1000
	v_add_u32_e32 v107, v128, v107
	ds_read_b128 v[144:147], v107 offset:0
	ds_read_b128 v[148:151], v107 offset:0x1000
	ds_read_b128 v[182:185], v107 offset:0x2000
	s_waitcnt lgkmcnt(5)
	s_nop 0
	v_mfma_f32_32x32x16_bf16 v[64:79], v[96:99], v[114:117], v[64:79]
	v_mfma_f32_32x32x16_bf16 v[32:47], v[96:99], v[118:121], v[32:47]
	v_mfma_f32_32x32x16_bf16 v[0:15], v[96:99], v[122:125], v[0:15]
	v_mfma_f32_32x32x16_bf16 v[48:63], v[110:113], v[118:121], v[48:63]
	v_mfma_f32_32x32x16_bf16 v[16:31], v[110:113], v[122:125], v[16:31]
	v_mfma_f32_32x32x16_bf16 v[80:95], v[110:113], v[114:117], v[80:95]
	s_waitcnt lgkmcnt(0)
	s_nop 0
	v_mfma_f32_32x32x16_bf16 v[64:79], v[130:133], v[144:147], v[64:79]
	v_mfma_f32_32x32x16_bf16 v[32:47], v[130:133], v[148:151], v[32:47]
	v_mfma_f32_32x32x16_bf16 v[0:15], v[130:133], v[182:185], v[0:15]
	v_mfma_f32_32x32x16_bf16 v[48:63], v[134:137], v[148:151], v[48:63]
	v_mfma_f32_32x32x16_bf16 v[16:31], v[134:137], v[182:185], v[16:31]
	v_mfma_f32_32x32x16_bf16 v[80:95], v[134:137], v[144:147], v[80:95]
	v_add_u32_e32 v96, s4, v106
	v_lshrrev_b32_e32 v128, 4, v101
	v_and_b32_e32 v112, 15, v100
	v_or_b32_e32 v100, v96, v128
	v_add_u32_e32 v105, s8, v105
	v_ashrrev_i32_e32 v101, 31, v100
	v_lshl_or_b32 v98, v112, 2, v105
	v_lshlrev_b64 v[106:107], 12, v[100:101]
	v_ashrrev_i32_e32 v99, 31, v98
	v_lshl_add_u64 v[106:107], s[40:41], 0, v[106:107]
	v_lshl_add_u64 v[110:111], v[98:99], 2, v[106:107]
	s_barrier
	v_add_co_u32_e32 v182, vcc, 0x20000, v110
	s_nop 1
	v_addc_co_u32_e32 v183, vcc, 0, v111, vcc
	global_load_dwordx4 v[184:187], v[182:183], off
	v_add_co_u32_e32 v182, vcc, 0x4000, v182
	s_nop 1
	v_addc_co_u32_e32 v183, vcc, 0, v183, vcc
	global_load_dwordx4 v[188:191], v[182:183], off
	v_add_co_u32_e32 v182, vcc, 0x4000, v182
	s_nop 1
	v_addc_co_u32_e32 v183, vcc, 0, v183, vcc
	global_load_dwordx4 v[192:195], v[182:183], off
	v_add_co_u32_e32 v182, vcc, 0x4000, v182
	s_nop 1
	v_addc_co_u32_e32 v183, vcc, 0, v183, vcc
	global_load_dwordx4 v[116:119], v[182:183], off
	v_add_co_u32_e32 v182, vcc, 0x4000, v182
	s_nop 1
	v_addc_co_u32_e32 v183, vcc, 0, v183, vcc
	global_load_dwordx4 v[120:123], v[182:183], off
	v_add_co_u32_e32 v182, vcc, 0x4000, v182
	s_nop 1
	v_addc_co_u32_e32 v183, vcc, 0, v183, vcc
	global_load_dwordx4 v[124:127], v[182:183], off
	v_add_co_u32_e32 v182, vcc, 0x4000, v182
	s_nop 1
	v_addc_co_u32_e32 v183, vcc, 0, v183, vcc
	global_load_dwordx4 v[130:133], v[182:183], off
	v_add_co_u32_e32 v182, vcc, 0x4000, v182
	s_nop 1
	v_addc_co_u32_e32 v183, vcc, 0, v183, vcc
	global_load_dwordx4 v[134:137], v[182:183], off
	s_movk_i32 s2, 0x2400
	s_cmp_lt_i32 s5, 22
	v_mul_lo_u32 v97, v103, s2
	s_cselect_b64 s[2:3], -1, 0
	s_cmp_gt_i32 s5, 21
	s_movk_i32 s5, 0x110
	v_and_b32_e32 v103, 16, v104
	v_mad_u32_u24 v104, v102, s5, v97
	v_add_u32_e32 v113, 0xfffff000, v96
	v_cndmask_b32_e64 v102, 0, 1, s[2:3]
	s_cselect_b64 s[2:3], -1, 0
	s_add_i32 s7, s4, 0xfffff000
	v_add_u32_e32 v104, v104, v103
	ds_write_b128 v104, v[64:67]
	ds_write_b128 v104, v[68:71] offset:32
	ds_write_b128 v104, v[72:75] offset:64
	ds_write_b128 v104, v[76:79] offset:96
	ds_write_b128 v104, v[80:83] offset:128
	ds_write_b128 v104, v[84:87] offset:160
	ds_write_b128 v104, v[88:91] offset:192
	ds_write_b128 v104, v[92:95] offset:224
	v_xor_b32_e32 v64, s7, v113
	s_movk_i32 s4, 0x400
	v_lshl_or_b32 v97, v112, 4, v97
	v_cmp_gt_u32_e32 vcc, s4, v64
	v_mad_u32_u24 v115, v128, s5, v97
	s_and_b64 s[4:5], s[2:3], vcc
	v_cndmask_b32_e64 v71, 0, 1, s[4:5]
	s_movk_i32 s4, 0x1000
	v_cmp_gt_i32_e32 vcc, s4, v100
	v_subrev_u32_e32 v114, s8, v98
	v_lshl_add_u32 v103, v114, 2, v167
	v_cndmask_b32_e32 v64, v71, v102, vcc
	v_and_b32_e32 v64, 1, v64
	v_cmp_eq_u32_e32 vcc, 1, v64
	v_ashrrev_i32_e32 v68, 6, v105
	s_mov_b32 s4, 0xc000
	v_cndmask_b32_e64 v64, v171, 0, vcc
	v_add_u32_e32 v70, v103, v64
	ds_read_b128 v[64:67], v115
	ds_read_b128 v[72:75], v70
	v_cmp_eq_u32_e64 s[36:37], 0, v112
	v_mad_i64_i32 v[68:69], s[4:5], v68, s4, 0
	s_and_b64 vcc, exec, s[0:1]
	s_waitcnt lgkmcnt(0)
	v_pk_fma_f32 v[66:67], v[66:67], v[74:75], v[200:201]
	v_pk_fma_f32 v[64:65], v[64:65], v[72:73], v[198:199]
	global_store_dwordx4 v[110:111], v[64:67], off
	s_cbranch_vccnz .LBB0_1439
	ds_read_b128 v[72:75], v70 offset:2048
	v_lshlrev_b64 v[76:77], 10, v[100:101]
	v_lshl_add_u64 v[76:77], v[76:77], 1, s[50:51]
	v_lshl_add_u64 v[76:77], v[98:99], 1, v[76:77]
	s_waitcnt lgkmcnt(0)
	v_pk_mul_f32 v[72:73], v[64:65], v[72:73]
	v_pk_mul_f32 v[64:65], v[64:65], v[64:65]
	v_pk_mul_f32 v[74:75], v[66:67], v[74:75]
	v_pk_mul_f32 v[66:67], v[66:67], v[66:67]
	v_add_f32_e32 v64, v64, v65
	v_add_f32_e32 v64, v66, v64
	v_add_f32_e32 v64, v67, v64
	v_cvt_pk_bf16_f32 v72, v72, v73
	v_cvt_pk_bf16_f32 v73, v74, v75
	v_add_f32_dpp v64, v64, v64 quad_perm:[1,0,3,2] row_mask:0xf bank_mask:0xf bound_ctrl:1
	global_store_dwordx2 v[76:77], v[72:73], off
	s_nop 0
	v_add_f32_dpp v64, v64, v64 quad_perm:[2,3,0,1] row_mask:0xf bank_mask:0xf bound_ctrl:1
	s_nop 1
	v_add_f32_dpp v64, v64, v64 row_half_mirror row_mask:0xf bank_mask:0xf bound_ctrl:1
	s_nop 1
	v_mov_b32_dpp v65, v64 row_mirror row_mask:0xf bank_mask:0xf bound_ctrl:1
	s_and_saveexec_b64 s[4:5], s[36:37]
	s_cbranch_execz .LBB0_1438
	v_lshl_add_u64 v[66:67], s[54:55], 0, v[68:69]
	v_lshl_add_u64 v[66:67], v[100:101], 2, v[66:67]
	v_add_f32_e32 v64, v64, v65
	global_store_dword v[66:67], v64, off

.LBB0_1439:
	v_or_b32_e32 v70, 4, v128
	v_or_b32_e32 v72, v96, v70
	v_ashrrev_i32_e32 v73, 31, v72
	v_lshlrev_b64 v[64:65], 12, v[72:73]
	v_lshl_add_u64 v[64:65], s[40:41], 0, v[64:65]
	v_lshl_add_u64 v[84:85], v[98:99], 2, v[64:65]
	s_movk_i32 s4, 0x1000
	v_mul_u32_u24_e32 v74, 0x110, v128
	v_cmp_gt_i32_e32 vcc, s4, v72
	v_add_u32_e32 v86, v74, v97
	s_nop 0
	v_cndmask_b32_e32 v74, v71, v102, vcc
	v_and_b32_e32 v74, 1, v74
	v_cmp_eq_u32_e32 vcc, 1, v74
	s_nop 1
	v_cndmask_b32_e64 v74, v171, 0, vcc
	v_add_u32_e32 v74, v103, v74
	ds_read_b128 v[76:79], v86 offset:1088
	ds_read_b128 v[80:83], v74
	s_and_b64 vcc, exec, s[0:1]
	s_waitcnt lgkmcnt(0)
	v_pk_fma_f32 v[66:67], v[78:79], v[82:83], v[204:205]
	v_pk_fma_f32 v[64:65], v[76:77], v[80:81], v[202:203]
	global_store_dwordx4 v[84:85], v[64:67], off
	s_cbranch_vccnz .LBB0_1443
	ds_read_b128 v[74:77], v74 offset:2048
	v_lshlrev_b64 v[72:73], 10, v[72:73]
	v_lshl_add_u64 v[72:73], v[72:73], 1, s[50:51]
	v_lshl_add_u64 v[72:73], v[98:99], 1, v[72:73]
	s_waitcnt lgkmcnt(0)
	v_pk_mul_f32 v[74:75], v[64:65], v[74:75]
	v_pk_mul_f32 v[64:65], v[64:65], v[64:65]
	v_pk_mul_f32 v[76:77], v[66:67], v[76:77]
	v_pk_mul_f32 v[66:67], v[66:67], v[66:67]
	v_add_f32_e32 v64, v64, v65
	v_add_f32_e32 v64, v66, v64
	v_add_f32_e32 v64, v67, v64
	v_cvt_pk_bf16_f32 v74, v74, v75
	v_cvt_pk_bf16_f32 v75, v76, v77
	v_add_f32_dpp v64, v64, v64 quad_perm:[1,0,3,2] row_mask:0xf bank_mask:0xf bound_ctrl:1
	global_store_dwordx2 v[72:73], v[74:75], off
	s_nop 0
	v_add_f32_dpp v64, v64, v64 quad_perm:[2,3,0,1] row_mask:0xf bank_mask:0xf bound_ctrl:1
	s_nop 1
	v_add_f32_dpp v64, v64, v64 row_half_mirror row_mask:0xf bank_mask:0xf bound_ctrl:1
	s_nop 1
	v_mov_b32_dpp v65, v64 row_mirror row_mask:0xf bank_mask:0xf bound_ctrl:1
	s_and_saveexec_b64 s[4:5], s[36:37]
	s_cbranch_execz .LBB0_1442
	v_ashrrev_i32_e32 v97, 31, v96
	v_lshl_add_u64 v[66:67], s[54:55], 0, v[68:69]
	v_lshl_add_u64 v[72:73], v[96:97], 0, v[128:129]
	v_lshl_add_u64 v[66:67], v[72:73], 2, v[66:67]
	v_add_f32_e32 v64, v64, v65
	global_store_dword v[66:67], v64, off offset:16

.LBB0_1443:
	v_or_b32_e32 v72, 8, v128
	v_or_b32_e32 v74, v96, v72
	v_ashrrev_i32_e32 v75, 31, v74
	v_lshlrev_b64 v[64:65], 12, v[74:75]
	v_lshl_add_u64 v[64:65], s[40:41], 0, v[64:65]
	v_lshl_add_u64 v[84:85], v[98:99], 2, v[64:65]
	s_movk_i32 s4, 0x1000
	v_cmp_gt_i32_e32 vcc, s4, v74
	s_nop 1
	v_cndmask_b32_e32 v73, v71, v102, vcc
	v_and_b32_e32 v73, 1, v73
	v_cmp_eq_u32_e32 vcc, 1, v73
	s_nop 1
	v_cndmask_b32_e64 v73, v171, 0, vcc
	v_add_u32_e32 v73, v103, v73
	ds_read_b128 v[76:79], v86 offset:2176
	ds_read_b128 v[80:83], v73
	s_and_b64 vcc, exec, s[0:1]
	s_waitcnt lgkmcnt(0)
	v_pk_fma_f32 v[66:67], v[78:79], v[82:83], v[208:209]
	v_pk_fma_f32 v[64:65], v[76:77], v[80:81], v[206:207]
	global_store_dwordx4 v[84:85], v[64:67], off
	s_cbranch_vccnz .LBB0_1447
	ds_read_b128 v[76:79], v73 offset:2048
	v_lshlrev_b64 v[74:75], 10, v[74:75]
	v_lshl_add_u64 v[74:75], v[74:75], 1, s[50:51]
	v_lshl_add_u64 v[74:75], v[98:99], 1, v[74:75]
	s_waitcnt lgkmcnt(0)
	v_pk_mul_f32 v[76:77], v[64:65], v[76:77]
	v_pk_mul_f32 v[64:65], v[64:65], v[64:65]
	v_pk_mul_f32 v[78:79], v[66:67], v[78:79]
	v_pk_mul_f32 v[66:67], v[66:67], v[66:67]
	v_add_f32_e32 v64, v64, v65
	v_add_f32_e32 v64, v66, v64
	v_add_f32_e32 v64, v67, v64
	v_cvt_pk_bf16_f32 v76, v76, v77
	v_cvt_pk_bf16_f32 v77, v78, v79
	v_add_f32_dpp v64, v64, v64 quad_perm:[1,0,3,2] row_mask:0xf bank_mask:0xf bound_ctrl:1
	global_store_dwordx2 v[74:75], v[76:77], off
	s_nop 0
	v_add_f32_dpp v64, v64, v64 quad_perm:[2,3,0,1] row_mask:0xf bank_mask:0xf bound_ctrl:1
	s_nop 1
	v_add_f32_dpp v64, v64, v64 row_half_mirror row_mask:0xf bank_mask:0xf bound_ctrl:1
	s_nop 1
	v_mov_b32_dpp v65, v64 row_mirror row_mask:0xf bank_mask:0xf bound_ctrl:1
	s_and_saveexec_b64 s[4:5], s[36:37]
	s_cbranch_execz .LBB0_1446
	v_ashrrev_i32_e32 v97, 31, v96
	v_lshl_add_u64 v[66:67], s[54:55], 0, v[68:69]
	v_lshl_add_u64 v[74:75], v[96:97], 0, v[128:129]
	v_lshl_add_u64 v[66:67], v[74:75], 2, v[66:67]
	v_add_f32_e32 v64, v64, v65
	global_store_dword v[66:67], v64, off offset:32

.LBB0_1447:
	v_or_b32_e32 v74, 12, v128
	v_or_b32_e32 v76, v96, v74
	v_ashrrev_i32_e32 v77, 31, v76
	v_lshlrev_b64 v[64:65], 12, v[76:77]
	v_lshl_add_u64 v[64:65], s[40:41], 0, v[64:65]
	v_lshl_add_u64 v[88:89], v[98:99], 2, v[64:65]
	s_movk_i32 s4, 0x1000
	v_cmp_gt_i32_e32 vcc, s4, v76
	s_nop 1
	v_cndmask_b32_e32 v73, v71, v102, vcc
	v_and_b32_e32 v73, 1, v73
	v_cmp_eq_u32_e32 vcc, 1, v73
	s_nop 1
	v_cndmask_b32_e64 v73, v171, 0, vcc
	v_add_u32_e32 v73, v103, v73
	ds_read_b128 v[78:81], v86 offset:3264
	ds_read_b128 v[82:85], v73
	s_and_b64 vcc, exec, s[0:1]
	s_waitcnt lgkmcnt(0)
	v_pk_fma_f32 v[66:67], v[80:81], v[84:85], v[212:213]
	v_pk_fma_f32 v[64:65], v[78:79], v[82:83], v[210:211]
	global_store_dwordx4 v[88:89], v[64:67], off
	s_cbranch_vccnz .LBB0_1451
	ds_read_b128 v[78:81], v73 offset:2048
	v_lshlrev_b64 v[76:77], 10, v[76:77]
	v_lshl_add_u64 v[76:77], v[76:77], 1, s[50:51]
	v_lshl_add_u64 v[76:77], v[98:99], 1, v[76:77]
	s_waitcnt lgkmcnt(0)
	v_pk_mul_f32 v[78:79], v[64:65], v[78:79]
	v_pk_mul_f32 v[64:65], v[64:65], v[64:65]
	v_pk_mul_f32 v[80:81], v[66:67], v[80:81]
	v_pk_mul_f32 v[66:67], v[66:67], v[66:67]
	v_add_f32_e32 v64, v64, v65
	v_add_f32_e32 v64, v66, v64
	v_add_f32_e32 v64, v67, v64
	v_cvt_pk_bf16_f32 v78, v78, v79
	v_cvt_pk_bf16_f32 v79, v80, v81
	v_add_f32_dpp v64, v64, v64 quad_perm:[1,0,3,2] row_mask:0xf bank_mask:0xf bound_ctrl:1
	global_store_dwordx2 v[76:77], v[78:79], off
	s_nop 0
	v_add_f32_dpp v64, v64, v64 quad_perm:[2,3,0,1] row_mask:0xf bank_mask:0xf bound_ctrl:1
	s_nop 1
	v_add_f32_dpp v64, v64, v64 row_half_mirror row_mask:0xf bank_mask:0xf bound_ctrl:1
	s_nop 1
	v_mov_b32_dpp v65, v64 row_mirror row_mask:0xf bank_mask:0xf bound_ctrl:1
	s_and_saveexec_b64 s[4:5], s[36:37]
	s_cbranch_execz .LBB0_1450
	v_ashrrev_i32_e32 v97, 31, v96
	v_lshl_add_u64 v[66:67], s[54:55], 0, v[68:69]
	v_lshl_add_u64 v[76:77], v[96:97], 0, v[128:129]
	v_lshl_add_u64 v[66:67], v[76:77], 2, v[66:67]
	v_add_f32_e32 v64, v64, v65
	global_store_dword v[66:67], v64, off offset:48

.LBB0_1451:
	v_or_b32_e32 v76, 16, v128
	v_or_b32_e32 v78, v96, v76
	v_ashrrev_i32_e32 v79, 31, v78
	v_lshlrev_b64 v[64:65], 12, v[78:79]
	v_lshl_add_u64 v[64:65], s[40:41], 0, v[64:65]
	v_lshl_add_u64 v[84:85], v[98:99], 2, v[64:65]
	s_movk_i32 s4, 0x1000
	v_cmp_gt_i32_e32 vcc, s4, v78
	s_nop 1
	v_cndmask_b32_e32 v73, v71, v102, vcc
	v_and_b32_e32 v73, 1, v73
	v_cmp_eq_u32_e32 vcc, 1, v73
	s_nop 1
	v_cndmask_b32_e64 v73, v171, 0, vcc
	v_add_u32_e32 v73, v103, v73
	ds_read_b128 v[80:83], v86 offset:4352
	ds_read_b128 v[88:91], v73
	s_and_b64 vcc, exec, s[0:1]
	s_waitcnt lgkmcnt(0)
	v_pk_fma_f32 v[66:67], v[82:83], v[90:91], v[216:217]
	v_pk_fma_f32 v[64:65], v[80:81], v[88:89], v[214:215]
	global_store_dwordx4 v[84:85], v[64:67], off
	s_cbranch_vccnz .LBB0_1455
	ds_read_b128 v[80:83], v73 offset:2048
	v_lshlrev_b64 v[78:79], 10, v[78:79]
	v_lshl_add_u64 v[78:79], v[78:79], 1, s[50:51]
	v_lshl_add_u64 v[78:79], v[98:99], 1, v[78:79]
	s_waitcnt lgkmcnt(0)
	v_pk_mul_f32 v[80:81], v[64:65], v[80:81]
	v_pk_mul_f32 v[64:65], v[64:65], v[64:65]
	v_pk_mul_f32 v[82:83], v[66:67], v[82:83]
	v_pk_mul_f32 v[66:67], v[66:67], v[66:67]
	v_add_f32_e32 v64, v64, v65
	v_add_f32_e32 v64, v66, v64
	v_add_f32_e32 v64, v67, v64
	v_cvt_pk_bf16_f32 v80, v80, v81
	v_cvt_pk_bf16_f32 v81, v82, v83
	v_add_f32_dpp v64, v64, v64 quad_perm:[1,0,3,2] row_mask:0xf bank_mask:0xf bound_ctrl:1
	global_store_dwordx2 v[78:79], v[80:81], off
	s_nop 0
	v_add_f32_dpp v64, v64, v64 quad_perm:[2,3,0,1] row_mask:0xf bank_mask:0xf bound_ctrl:1
	s_nop 1
	v_add_f32_dpp v64, v64, v64 row_half_mirror row_mask:0xf bank_mask:0xf bound_ctrl:1
	s_nop 1
	v_mov_b32_dpp v65, v64 row_mirror row_mask:0xf bank_mask:0xf bound_ctrl:1
	s_and_saveexec_b64 s[4:5], s[36:37]
	s_cbranch_execz .LBB0_1454
	v_ashrrev_i32_e32 v97, 31, v96
	v_lshl_add_u64 v[66:67], s[54:55], 0, v[68:69]
	v_lshl_add_u64 v[78:79], v[96:97], 0, v[128:129]
	v_lshl_add_u64 v[66:67], v[78:79], 2, v[66:67]
	v_add_f32_e32 v64, v64, v65
	global_store_dword v[66:67], v64, off offset:64

.LBB0_1455:
	v_or_b32_e32 v78, 20, v128
	v_or_b32_e32 v80, v96, v78
	v_ashrrev_i32_e32 v81, 31, v80
	v_lshlrev_b64 v[64:65], 12, v[80:81]
	v_lshl_add_u64 v[64:65], s[40:41], 0, v[64:65]
	v_lshl_add_u64 v[92:93], v[98:99], 2, v[64:65]
	s_movk_i32 s4, 0x1000
	v_cmp_gt_i32_e32 vcc, s4, v80
	s_nop 1
	v_cndmask_b32_e32 v73, v71, v102, vcc
	v_and_b32_e32 v73, 1, v73
	v_cmp_eq_u32_e32 vcc, 1, v73
	s_nop 1
	v_cndmask_b32_e64 v73, v171, 0, vcc
	v_add_u32_e32 v73, v103, v73
	ds_read_b128 v[82:85], v86 offset:5440
	ds_read_b128 v[88:91], v73
	s_and_b64 vcc, exec, s[0:1]
	s_waitcnt lgkmcnt(0)
	v_pk_fma_f32 v[66:67], v[84:85], v[90:91], v[220:221]
	v_pk_fma_f32 v[64:65], v[82:83], v[88:89], v[218:219]
	global_store_dwordx4 v[92:93], v[64:67], off
	s_cbranch_vccnz .LBB0_1459
	ds_read_b128 v[82:85], v73 offset:2048
	v_lshlrev_b64 v[80:81], 10, v[80:81]
	v_lshl_add_u64 v[80:81], v[80:81], 1, s[50:51]
	v_lshl_add_u64 v[80:81], v[98:99], 1, v[80:81]
	s_waitcnt lgkmcnt(0)
	v_pk_mul_f32 v[82:83], v[64:65], v[82:83]
	v_pk_mul_f32 v[64:65], v[64:65], v[64:65]
	v_pk_mul_f32 v[84:85], v[66:67], v[84:85]
	v_pk_mul_f32 v[66:67], v[66:67], v[66:67]
	v_add_f32_e32 v64, v64, v65
	v_add_f32_e32 v64, v66, v64
	v_add_f32_e32 v64, v67, v64
	v_cvt_pk_bf16_f32 v82, v82, v83
	v_cvt_pk_bf16_f32 v83, v84, v85
	v_add_f32_dpp v64, v64, v64 quad_perm:[1,0,3,2] row_mask:0xf bank_mask:0xf bound_ctrl:1
	global_store_dwordx2 v[80:81], v[82:83], off
	s_nop 0
	v_add_f32_dpp v64, v64, v64 quad_perm:[2,3,0,1] row_mask:0xf bank_mask:0xf bound_ctrl:1
	s_nop 1
	v_add_f32_dpp v64, v64, v64 row_half_mirror row_mask:0xf bank_mask:0xf bound_ctrl:1
	s_nop 1
	v_mov_b32_dpp v65, v64 row_mirror row_mask:0xf bank_mask:0xf bound_ctrl:1
	s_and_saveexec_b64 s[4:5], s[36:37]
	s_cbranch_execz .LBB0_1458
	v_ashrrev_i32_e32 v97, 31, v96
	v_lshl_add_u64 v[66:67], s[54:55], 0, v[68:69]
	v_lshl_add_u64 v[80:81], v[96:97], 0, v[128:129]
	v_lshl_add_u64 v[66:67], v[80:81], 2, v[66:67]
	v_add_f32_e32 v64, v64, v65
	global_store_dword v[66:67], v64, off offset:80

.LBB0_1459:
	v_or_b32_e32 v80, 24, v128
	v_or_b32_e32 v82, v96, v80
	v_ashrrev_i32_e32 v83, 31, v82
	v_lshlrev_b64 v[64:65], 12, v[82:83]
	v_lshl_add_u64 v[64:65], s[40:41], 0, v[64:65]
	v_lshl_add_u64 v[84:85], v[98:99], 2, v[64:65]
	s_movk_i32 s4, 0x1000
	v_cmp_gt_i32_e32 vcc, s4, v82
	s_nop 1
	v_cndmask_b32_e32 v73, v71, v102, vcc
	v_and_b32_e32 v73, 1, v73
	v_cmp_eq_u32_e32 vcc, 1, v73
	s_nop 1
	v_cndmask_b32_e64 v73, v171, 0, vcc
	v_add_u32_e32 v73, v103, v73
	ds_read_b128 v[88:91], v86 offset:6528
	ds_read_b128 v[92:95], v73
	s_and_b64 vcc, exec, s[0:1]
	s_waitcnt lgkmcnt(0)
	v_pk_fma_f32 v[66:67], v[90:91], v[94:95], v[224:225]
	v_pk_fma_f32 v[64:65], v[88:89], v[92:93], v[222:223]
	global_store_dwordx4 v[84:85], v[64:67], off
	s_cbranch_vccnz .LBB0_1463
	ds_read_b128 v[88:91], v73 offset:2048
	v_lshlrev_b64 v[82:83], 10, v[82:83]
	v_lshl_add_u64 v[82:83], v[82:83], 1, s[50:51]
	v_lshl_add_u64 v[82:83], v[98:99], 1, v[82:83]
	s_waitcnt lgkmcnt(0)
	v_pk_mul_f32 v[88:89], v[64:65], v[88:89]
	v_pk_mul_f32 v[64:65], v[64:65], v[64:65]
	v_pk_mul_f32 v[84:85], v[66:67], v[90:91]
	v_pk_mul_f32 v[66:67], v[66:67], v[66:67]
	v_add_f32_e32 v64, v64, v65
	v_add_f32_e32 v64, v66, v64
	v_add_f32_e32 v64, v67, v64
	v_cvt_pk_bf16_f32 v88, v88, v89
	v_cvt_pk_bf16_f32 v89, v84, v85
	v_add_f32_dpp v64, v64, v64 quad_perm:[1,0,3,2] row_mask:0xf bank_mask:0xf bound_ctrl:1
	global_store_dwordx2 v[82:83], v[88:89], off
	s_nop 0
	v_add_f32_dpp v64, v64, v64 quad_perm:[2,3,0,1] row_mask:0xf bank_mask:0xf bound_ctrl:1
	s_nop 1
	v_add_f32_dpp v64, v64, v64 row_half_mirror row_mask:0xf bank_mask:0xf bound_ctrl:1
	s_nop 1
	v_mov_b32_dpp v65, v64 row_mirror row_mask:0xf bank_mask:0xf bound_ctrl:1
	s_and_saveexec_b64 s[4:5], s[36:37]
	s_cbranch_execz .LBB0_1462
	v_ashrrev_i32_e32 v97, 31, v96
	v_lshl_add_u64 v[66:67], s[54:55], 0, v[68:69]
	v_lshl_add_u64 v[82:83], v[96:97], 0, v[128:129]
	v_lshl_add_u64 v[66:67], v[82:83], 2, v[66:67]
	v_add_f32_e32 v64, v64, v65
	global_store_dword v[66:67], v64, off offset:96

.LBB0_1463:
	v_or_b32_e32 v82, 28, v128
	v_or_b32_e32 v84, v96, v82
	v_ashrrev_i32_e32 v85, 31, v84
	v_lshlrev_b64 v[64:65], 12, v[84:85]
	v_lshl_add_u64 v[64:65], s[40:41], 0, v[64:65]
	v_lshl_add_u64 v[100:101], v[98:99], 2, v[64:65]
	s_movk_i32 s4, 0x1000
	v_cmp_gt_i32_e32 vcc, s4, v84
	s_nop 1
	v_cndmask_b32_e32 v71, v71, v102, vcc
	v_and_b32_e32 v71, 1, v71
	v_cmp_eq_u32_e32 vcc, 1, v71
	s_nop 1
	v_cndmask_b32_e64 v71, v171, 0, vcc
	v_add_u32_e32 v71, v103, v71
	ds_read_b128 v[88:91], v86 offset:7616
	ds_read_b128 v[92:95], v71
	s_and_b64 vcc, exec, s[0:1]
	s_waitcnt lgkmcnt(0)
	v_pk_fma_f32 v[66:67], v[90:91], v[94:95], v[228:229]
	v_pk_fma_f32 v[64:65], v[88:89], v[92:93], v[226:227]
	global_store_dwordx4 v[100:101], v[64:67], off
	s_cbranch_vccnz .LBB0_1467
	ds_read_b128 v[88:91], v71 offset:2048
	v_lshlrev_b64 v[84:85], 10, v[84:85]
	v_lshl_add_u64 v[84:85], v[84:85], 1, s[50:51]
	v_lshl_add_u64 v[84:85], v[98:99], 1, v[84:85]
	s_waitcnt lgkmcnt(0)
	v_pk_mul_f32 v[88:89], v[64:65], v[88:89]
	v_pk_mul_f32 v[64:65], v[64:65], v[64:65]
	v_pk_mul_f32 v[90:91], v[66:67], v[90:91]
	v_pk_mul_f32 v[66:67], v[66:67], v[66:67]
	v_add_f32_e32 v64, v64, v65
	v_add_f32_e32 v64, v66, v64
	v_add_f32_e32 v64, v67, v64
	v_cvt_pk_bf16_f32 v88, v88, v89
	v_cvt_pk_bf16_f32 v89, v90, v91
	v_add_f32_dpp v64, v64, v64 quad_perm:[1,0,3,2] row_mask:0xf bank_mask:0xf bound_ctrl:1
	global_store_dwordx2 v[84:85], v[88:89], off
	s_nop 0
	v_add_f32_dpp v64, v64, v64 quad_perm:[2,3,0,1] row_mask:0xf bank_mask:0xf bound_ctrl:1
	s_nop 1
	v_add_f32_dpp v64, v64, v64 row_half_mirror row_mask:0xf bank_mask:0xf bound_ctrl:1
	s_nop 1
	v_mov_b32_dpp v65, v64 row_mirror row_mask:0xf bank_mask:0xf bound_ctrl:1
	s_and_saveexec_b64 s[4:5], s[36:37]
	s_cbranch_execz .LBB0_1466
	v_ashrrev_i32_e32 v97, 31, v96
	v_lshl_add_u64 v[66:67], s[54:55], 0, v[68:69]
	v_lshl_add_u64 v[84:85], v[96:97], 0, v[128:129]
	v_lshl_add_u64 v[66:67], v[84:85], 2, v[66:67]
	v_add_f32_e32 v64, v64, v65
	global_store_dword v[66:67], v64, off offset:112
